# mixer-branch GEMM tile hand-written: K tiles and gate tiles by direct global->LDS loads in one stream, gating from LDS
# speedup vs baseline: 1.0098x; 1.0040x over previous
.LBB0_212:
	v_mov_b32_e32 v0, v1
	v_mbcnt_lo_u32_b32 v0, -1, v0
	v_mbcnt_hi_u32_b32 v0, -1, v0
	v_add_u32_e32 v132, s80, v0
	s_waitcnt vmcnt(0) lgkmcnt(0)
	s_barrier
	v_readlane_b32 s50, v252, 18
	v_readlane_b32 s51, v252, 19
	s_lshl_b32 s23, s22, 4
	s_and_b32 s23, s23, 0xffffff80
	s_and_b32 s24, s22, 7
	s_lshl_b32 s24, s24, 7
	s_lshl_b32 s25, s24, 1
	s_add_u32 s36, s50, 0xf525000
	s_addc_u32 s37, s51, 0
	s_mov_b64 s[38:39], s[4:5]
	s_mov_b64 s[40:41], s[90:91]
	s_add_u32 s42, s90, 0x80
	s_addc_u32 s43, s91, 0
	s_lshl_b32 vcc_lo, s80, 4
	v_lshrrev_b32_e32 v246, 3, v132
	v_and_b32_e32 v247, 7, v132
	v_bfe_u32 v248, v132, 4, 3
	v_xor_b32_e32 v247, v247, v248
	v_lshlrev_b32_e32 v247, 4, v247
	v_add_u32_e32 v0, s23, v246
	v_lshl_or_b32 v206, v0, 10, v247
	v_add_u32_e32 v207, 0x8000, v206
	v_add_u32_e32 v208, 0x10000, v206
	v_add_u32_e32 v209, 0x18000, v206
	v_mul_u32_u24_e32 v0, 0x1800, v0
	v_add3_u32 v222, v0, s25, v247
	v_add_u32_e32 v223, 0x30000, v222
	v_add_u32_e32 v224, 0x60000, v222
	v_add_u32_e32 v225, 0x90000, v222
	v_add_u32_e32 v0, s24, v246
	v_mul_u32_u24_e32 v0, 0xc00, v0
	v_add_u32_e32 v210, v0, v247
	v_add_u32_e32 v211, 0x18000, v210
	v_add_u32_e32 v212, 0x30000, v210
	v_add_u32_e32 v213, 0x48000, v210
	s_mov_b32 m0, vcc_lo
	s_nop 0
	global_load_lds_dwordx4 v206, s[36:37]
	s_add_u32 m0, vcc_lo, 0x1000
	s_nop 0
	global_load_lds_dwordx4 v207, s[36:37]
	s_add_u32 m0, vcc_lo, 0x2000
	s_nop 0
	global_load_lds_dwordx4 v208, s[36:37]
	s_add_u32 m0, vcc_lo, 0x3000
	s_nop 0
	global_load_lds_dwordx4 v209, s[36:37]
	s_add_u32 m0, vcc_lo, 0x4000
	s_nop 0
	global_load_lds_dwordx4 v210, s[38:39]
	s_add_u32 m0, vcc_lo, 0x5000
	s_nop 0
	global_load_lds_dwordx4 v211, s[38:39]
	s_add_u32 m0, vcc_lo, 0x6000
	s_nop 0
	global_load_lds_dwordx4 v212, s[38:39]
	s_add_u32 m0, vcc_lo, 0x7000
	s_nop 0
	global_load_lds_dwordx4 v213, s[38:39]
	s_add_u32 s36, s36, 0x80
	s_addc_u32 s37, s37, 0
	s_add_u32 s38, s38, 0x80
	s_addc_u32 s39, s39, 0
	v_bfe_u32 v246, v132, 5, 1
	v_bfe_u32 v247, v132, 1, 3
	v_xor_b32_e32 v246, v246, v247
	v_lshlrev_b32_e32 v246, 4, v246
	v_lshrrev_b32_e32 v247, 1, v132
	v_and_b32_e32 v247, 64, v247
	v_and_b32_e32 v248, 31, v132
	v_or_b32_e32 v247, v247, v248
	v_lshl_or_b32 v236, v247, 7, v246
	v_and_b32_e32 v247, 0x5f, v132
	v_lshl_or_b32 v240, v247, 7, v246
	v_add_u32_e32 v240, 0x4000, v240
	v_xor_b32_e32 v237, 0x20, v236
	v_xor_b32_e32 v241, 0x20, v240
	v_xor_b32_e32 v238, 0x40, v236
	v_xor_b32_e32 v242, 0x40, v240
	v_xor_b32_e32 v239, 0x60, v236
	v_xor_b32_e32 v243, 0x60, v240
	v_lshrrev_b32_e32 v246, 1, v132
	v_and_b32_e32 v246, 64, v246
	v_lshrrev_b32_e32 v247, 3, v132
	v_and_or_b32 v246, v247, 4, v246
	v_bfe_u32 v247, v132, 3, 2
	v_lshrrev_b32_e32 v248, 4, v132
	v_and_b32_e32 v248, 2, v248
	v_xor_b32_e32 v247, v247, v248
	v_and_b32_e32 v248, 7, v132
	v_lshlrev_b32_e32 v248, 1, v248
	v_lshl_or_b32 v247, v247, 4, v248
	v_lshl_or_b32 v244, v246, 7, v247
	v_bfe_u32 v247, v132, 6, 1
	v_lshl_or_b32 v244, v247, 14, v244
	v_xor_b32_e32 v245, 16, v244
	v_ashrrev_i32_e32 v184, 4, v132
	v_lshlrev_b32_e32 v185, 3, v132
	v_and_b32_e32 v185, 0x78, v185
	v_mul_u32_u24_e32 v98, 0x110, v246
	v_lshlrev_b32_e32 v247, 1, v132
	v_and_b32_e32 v247, 0x80, v247
	v_and_b32_e32 v248, 31, v132
	v_lshl_or_b32 v247, v248, 1, v247
	v_add_u32_e32 v98, v98, v247
	v_mul_u32_u24_e32 v133, 0x110, v184
	v_lshl_add_u32 v133, v185, 1, v133
	v_mov_b32_e32 v166, 0
	v_mov_b32_e32 v167, 0
	v_mov_b32_e32 v164, 0
	v_mov_b32_e32 v165, 0
	v_mov_b32_e32 v162, 0
	v_mov_b32_e32 v163, 0
	v_mov_b32_e32 v160, 0
	v_mov_b32_e32 v161, 0
	v_mov_b32_e32 v158, 0
	v_mov_b32_e32 v159, 0
	v_mov_b32_e32 v156, 0
	v_mov_b32_e32 v157, 0
	v_mov_b32_e32 v154, 0
	v_mov_b32_e32 v155, 0
	v_mov_b32_e32 v152, 0
	v_mov_b32_e32 v153, 0
	v_mov_b32_e32 v150, 0
	v_mov_b32_e32 v151, 0
	v_mov_b32_e32 v148, 0
	v_mov_b32_e32 v149, 0
	v_mov_b32_e32 v146, 0
	v_mov_b32_e32 v147, 0
	v_mov_b32_e32 v142, 0
	v_mov_b32_e32 v143, 0
	v_mov_b32_e32 v140, 0
	v_mov_b32_e32 v141, 0
	v_mov_b32_e32 v138, 0
	v_mov_b32_e32 v139, 0
	v_mov_b32_e32 v136, 0
	v_mov_b32_e32 v137, 0
	v_mov_b32_e32 v134, 0
	v_mov_b32_e32 v135, 0
	v_mov_b32_e32 v130, 0
	v_mov_b32_e32 v131, 0
	v_mov_b32_e32 v128, 0
	v_mov_b32_e32 v129, 0
	v_mov_b32_e32 v126, 0
	v_mov_b32_e32 v127, 0
	v_mov_b32_e32 v124, 0
	v_mov_b32_e32 v125, 0
	v_mov_b32_e32 v122, 0
	v_mov_b32_e32 v123, 0
	v_mov_b32_e32 v120, 0
	v_mov_b32_e32 v121, 0
	v_mov_b32_e32 v118, 0
	v_mov_b32_e32 v119, 0
	v_mov_b32_e32 v116, 0
	v_mov_b32_e32 v117, 0
	v_mov_b32_e32 v114, 0
	v_mov_b32_e32 v115, 0
	v_mov_b32_e32 v112, 0
	v_mov_b32_e32 v113, 0
	v_mov_b32_e32 v110, 0
	v_mov_b32_e32 v111, 0
	v_mov_b32_e32 v108, 0
	v_mov_b32_e32 v109, 0
	v_mov_b32_e32 v106, 0
	v_mov_b32_e32 v107, 0
	v_mov_b32_e32 v104, 0
	v_mov_b32_e32 v105, 0
	v_mov_b32_e32 v102, 0
	v_mov_b32_e32 v103, 0
	v_mov_b32_e32 v100, 0
	v_mov_b32_e32 v101, 0
	s_waitcnt vmcnt(0)
	s_barrier
	s_add_u32 m0, vcc_lo, 0x8000
	ds_read_b128 v[66:69], v236
	global_load_lds_dwordx4 v206, s[36:37]
	s_setprio 3
	ds_read_b128 v[70:73], v240
	s_add_u32 m0, vcc_lo, 0x9000
	ds_read_b128 v[74:77], v240 offset:4096
	global_load_lds_dwordx4 v207, s[36:37]
	ds_read_b128 v[78:81], v236 offset:4096
	s_add_u32 m0, vcc_lo, 0xa000
	ds_read_b128 v[82:85], v237
	global_load_lds_dwordx4 v208, s[36:37]
	ds_read_b128 v[86:89], v241
	s_add_u32 m0, vcc_lo, 0xb000
	ds_read_b128 v[90:93], v241 offset:4096
	global_load_lds_dwordx4 v209, s[36:37]
	ds_read_b128 v[94:97], v237 offset:4096
	s_waitcnt lgkmcnt(6)
	v_mfma_f32_32x32x16_bf16 v[50:65], v[66:69], v[70:73], 0
	s_add_u32 m0, vcc_lo, 0xc000
	ds_read_b128 v[168:171], v238
	global_load_lds_dwordx4 v210, s[38:39]
	s_waitcnt lgkmcnt(5)
	v_mfma_f32_32x32x16_bf16 v[18:33], v[78:81], v[70:73], 0
	ds_read_b128 v[172:175], v242
	v_mfma_f32_32x32x16_bf16 v[2:17], v[78:81], v[74:77], 0
	s_add_u32 m0, vcc_lo, 0xd000
	ds_read_b128 v[176:179], v242 offset:4096
	global_load_lds_dwordx4 v211, s[38:39]
	v_mfma_f32_32x32x16_bf16 v[34:49], v[66:69], v[74:77], 0
	ds_read_b128 v[180:183], v238 offset:4096
	s_waitcnt lgkmcnt(6)
	v_mfma_f32_32x32x16_bf16 v[50:65], v[82:85], v[86:89], v[50:65]
	s_add_u32 m0, vcc_lo, 0xe000
	ds_read_b128 v[190:193], v239
	global_load_lds_dwordx4 v212, s[38:39]
	s_waitcnt lgkmcnt(5)
	v_mfma_f32_32x32x16_bf16 v[18:33], v[94:97], v[86:89], v[18:33]
	ds_read_b128 v[194:197], v243
	v_mfma_f32_32x32x16_bf16 v[2:17], v[94:97], v[90:93], v[2:17]
	s_add_u32 m0, vcc_lo, 0xf000
	ds_read_b128 v[198:201], v243 offset:4096
	global_load_lds_dwordx4 v213, s[38:39]
	v_mfma_f32_32x32x16_bf16 v[34:49], v[82:85], v[90:93], v[34:49]
	ds_read_b128 v[202:205], v239 offset:4096
	s_add_u32 s36, s36, 0x80
	s_addc_u32 s37, s37, 0
	s_add_u32 s38, s38, 0x80
	s_addc_u32 s39, s39, 0
	s_waitcnt vmcnt(0) lgkmcnt(0)
	s_barrier
	v_mfma_f32_32x32x16_bf16 v[50:65], v[168:171], v[172:175], v[50:65]
	s_mov_b32 m0, vcc_lo
	ds_read_b128 v[66:69], v236 offset:32768
	global_load_lds_dwordx4 v206, s[36:37]
	s_setprio 3
	v_mfma_f32_32x32x16_bf16 v[18:33], v[180:183], v[172:175], v[18:33]
	ds_read_b128 v[70:73], v240 offset:32768
	v_mfma_f32_32x32x16_bf16 v[2:17], v[180:183], v[176:179], v[2:17]
	s_add_u32 m0, vcc_lo, 0x1000
	ds_read_b128 v[74:77], v240 offset:36864
	global_load_lds_dwordx4 v207, s[36:37]
	v_mfma_f32_32x32x16_bf16 v[34:49], v[168:171], v[176:179], v[34:49]
	ds_read_b128 v[78:81], v236 offset:36864
	v_mfma_f32_32x32x16_bf16 v[50:65], v[190:193], v[194:197], v[50:65]
	s_add_u32 m0, vcc_lo, 0x2000
	ds_read_b128 v[82:85], v237 offset:32768
	global_load_lds_dwordx4 v208, s[36:37]
	v_mfma_f32_32x32x16_bf16 v[18:33], v[202:205], v[194:197], v[18:33]
	ds_read_b128 v[86:89], v241 offset:32768
	v_mfma_f32_32x32x16_bf16 v[2:17], v[202:205], v[198:201], v[2:17]
	s_add_u32 m0, vcc_lo, 0x3000
	ds_read_b128 v[90:93], v241 offset:36864
	global_load_lds_dwordx4 v209, s[36:37]
	v_mfma_f32_32x32x16_bf16 v[34:49], v[190:193], v[198:201], v[34:49]
	ds_read_b128 v[94:97], v237 offset:36864
	s_waitcnt lgkmcnt(6)
	v_mfma_f32_32x32x16_bf16 v[50:65], v[66:69], v[70:73], v[50:65]
	s_add_u32 m0, vcc_lo, 0x4000
	ds_read_b128 v[168:171], v238 offset:32768
	global_load_lds_dwordx4 v210, s[38:39]
	s_waitcnt lgkmcnt(5)
	v_mfma_f32_32x32x16_bf16 v[18:33], v[78:81], v[70:73], v[18:33]
	ds_read_b128 v[172:175], v242 offset:32768
	v_mfma_f32_32x32x16_bf16 v[2:17], v[78:81], v[74:77], v[2:17]
	s_add_u32 m0, vcc_lo, 0x5000
	ds_read_b128 v[176:179], v242 offset:36864
	global_load_lds_dwordx4 v211, s[38:39]
	v_mfma_f32_32x32x16_bf16 v[34:49], v[66:69], v[74:77], v[34:49]
	ds_read_b128 v[180:183], v238 offset:36864
	s_waitcnt lgkmcnt(6)
	v_mfma_f32_32x32x16_bf16 v[50:65], v[82:85], v[86:89], v[50:65]
	s_add_u32 m0, vcc_lo, 0x6000
	ds_read_b128 v[190:193], v239 offset:32768
	global_load_lds_dwordx4 v212, s[38:39]
	s_waitcnt lgkmcnt(5)
	v_mfma_f32_32x32x16_bf16 v[18:33], v[94:97], v[86:89], v[18:33]
	ds_read_b128 v[194:197], v243 offset:32768
	v_mfma_f32_32x32x16_bf16 v[2:17], v[94:97], v[90:93], v[2:17]
	s_add_u32 m0, vcc_lo, 0x7000
	ds_read_b128 v[198:201], v243 offset:36864
	global_load_lds_dwordx4 v213, s[38:39]
	v_mfma_f32_32x32x16_bf16 v[34:49], v[82:85], v[90:93], v[34:49]
	ds_read_b128 v[202:205], v239 offset:36864
	s_add_u32 s36, s36, 0x80
	s_addc_u32 s37, s37, 0
	s_add_u32 s38, s38, 0x80
	s_addc_u32 s39, s39, 0
	s_waitcnt vmcnt(0) lgkmcnt(0)
	s_barrier
	v_mfma_f32_32x32x16_bf16 v[50:65], v[168:171], v[172:175], v[50:65]
	s_add_u32 m0, vcc_lo, 0x8000
	ds_read_b128 v[66:69], v236
	global_load_lds_dwordx4 v206, s[36:37]
	s_setprio 3
	v_mfma_f32_32x32x16_bf16 v[18:33], v[180:183], v[172:175], v[18:33]
	ds_read_b128 v[70:73], v240
	v_mfma_f32_32x32x16_bf16 v[2:17], v[180:183], v[176:179], v[2:17]
	s_add_u32 m0, vcc_lo, 0x9000
	ds_read_b128 v[74:77], v240 offset:4096
	global_load_lds_dwordx4 v207, s[36:37]
	v_mfma_f32_32x32x16_bf16 v[34:49], v[168:171], v[176:179], v[34:49]
	ds_read_b128 v[78:81], v236 offset:4096
	v_mfma_f32_32x32x16_bf16 v[50:65], v[190:193], v[194:197], v[50:65]
	s_add_u32 m0, vcc_lo, 0xa000
	ds_read_b128 v[82:85], v237
	global_load_lds_dwordx4 v208, s[36:37]
	v_mfma_f32_32x32x16_bf16 v[18:33], v[202:205], v[194:197], v[18:33]
	ds_read_b128 v[86:89], v241
	v_mfma_f32_32x32x16_bf16 v[2:17], v[202:205], v[198:201], v[2:17]
	s_add_u32 m0, vcc_lo, 0xb000
	ds_read_b128 v[90:93], v241 offset:4096
	global_load_lds_dwordx4 v209, s[36:37]
	v_mfma_f32_32x32x16_bf16 v[34:49], v[190:193], v[198:201], v[34:49]
	ds_read_b128 v[94:97], v237 offset:4096
	s_waitcnt lgkmcnt(6)
	v_mfma_f32_32x32x16_bf16 v[50:65], v[66:69], v[70:73], v[50:65]
	s_add_u32 m0, vcc_lo, 0xc000
	ds_read_b128 v[168:171], v238
	global_load_lds_dwordx4 v210, s[38:39]
	s_waitcnt lgkmcnt(5)
	v_mfma_f32_32x32x16_bf16 v[18:33], v[78:81], v[70:73], v[18:33]
	ds_read_b128 v[172:175], v242
	v_mfma_f32_32x32x16_bf16 v[2:17], v[78:81], v[74:77], v[2:17]
	s_add_u32 m0, vcc_lo, 0xd000
	ds_read_b128 v[176:179], v242 offset:4096
	global_load_lds_dwordx4 v211, s[38:39]
	v_mfma_f32_32x32x16_bf16 v[34:49], v[66:69], v[74:77], v[34:49]
	ds_read_b128 v[180:183], v238 offset:4096
	s_waitcnt lgkmcnt(6)
	v_mfma_f32_32x32x16_bf16 v[50:65], v[82:85], v[86:89], v[50:65]
	s_add_u32 m0, vcc_lo, 0xe000
	ds_read_b128 v[190:193], v239
	global_load_lds_dwordx4 v212, s[38:39]
	s_waitcnt lgkmcnt(5)
	v_mfma_f32_32x32x16_bf16 v[18:33], v[94:97], v[86:89], v[18:33]
	ds_read_b128 v[194:197], v243
	v_mfma_f32_32x32x16_bf16 v[2:17], v[94:97], v[90:93], v[2:17]
	s_add_u32 m0, vcc_lo, 0xf000
	ds_read_b128 v[198:201], v243 offset:4096
	global_load_lds_dwordx4 v213, s[38:39]
	v_mfma_f32_32x32x16_bf16 v[34:49], v[82:85], v[90:93], v[34:49]
	ds_read_b128 v[202:205], v239 offset:4096
	s_add_u32 s36, s36, 0x80
	s_addc_u32 s37, s37, 0
	s_add_u32 s38, s38, 0x80
	s_addc_u32 s39, s39, 0
	s_waitcnt vmcnt(0) lgkmcnt(0)
	s_barrier
	v_mfma_f32_32x32x16_bf16 v[50:65], v[168:171], v[172:175], v[50:65]
	s_mov_b32 m0, vcc_lo
	ds_read_b128 v[66:69], v236 offset:32768
	global_load_lds_dwordx4 v206, s[36:37]
	s_setprio 3
	v_mfma_f32_32x32x16_bf16 v[18:33], v[180:183], v[172:175], v[18:33]
	ds_read_b128 v[70:73], v240 offset:32768
	v_mfma_f32_32x32x16_bf16 v[2:17], v[180:183], v[176:179], v[2:17]
	s_add_u32 m0, vcc_lo, 0x1000
	ds_read_b128 v[74:77], v240 offset:36864
	global_load_lds_dwordx4 v207, s[36:37]
	v_mfma_f32_32x32x16_bf16 v[34:49], v[168:171], v[176:179], v[34:49]
	ds_read_b128 v[78:81], v236 offset:36864
	v_mfma_f32_32x32x16_bf16 v[50:65], v[190:193], v[194:197], v[50:65]
	s_add_u32 m0, vcc_lo, 0x2000
	ds_read_b128 v[82:85], v237 offset:32768
	global_load_lds_dwordx4 v208, s[36:37]
	v_mfma_f32_32x32x16_bf16 v[18:33], v[202:205], v[194:197], v[18:33]
	ds_read_b128 v[86:89], v241 offset:32768
	v_mfma_f32_32x32x16_bf16 v[2:17], v[202:205], v[198:201], v[2:17]
	s_add_u32 m0, vcc_lo, 0x3000
	ds_read_b128 v[90:93], v241 offset:36864
	global_load_lds_dwordx4 v209, s[36:37]
	v_mfma_f32_32x32x16_bf16 v[34:49], v[190:193], v[198:201], v[34:49]
	ds_read_b128 v[94:97], v237 offset:36864
	s_waitcnt lgkmcnt(6)
	v_mfma_f32_32x32x16_bf16 v[50:65], v[66:69], v[70:73], v[50:65]
	s_add_u32 m0, vcc_lo, 0x4000
	ds_read_b128 v[168:171], v238 offset:32768
	global_load_lds_dwordx4 v210, s[38:39]
	s_waitcnt lgkmcnt(5)
	v_mfma_f32_32x32x16_bf16 v[18:33], v[78:81], v[70:73], v[18:33]
	ds_read_b128 v[172:175], v242 offset:32768
	v_mfma_f32_32x32x16_bf16 v[2:17], v[78:81], v[74:77], v[2:17]
	s_add_u32 m0, vcc_lo, 0x5000
	ds_read_b128 v[176:179], v242 offset:36864
	global_load_lds_dwordx4 v211, s[38:39]
	v_mfma_f32_32x32x16_bf16 v[34:49], v[66:69], v[74:77], v[34:49]
	ds_read_b128 v[180:183], v238 offset:36864
	s_waitcnt lgkmcnt(6)
	v_mfma_f32_32x32x16_bf16 v[50:65], v[82:85], v[86:89], v[50:65]
	s_add_u32 m0, vcc_lo, 0x6000
	ds_read_b128 v[190:193], v239 offset:32768
	global_load_lds_dwordx4 v212, s[38:39]
	s_waitcnt lgkmcnt(5)
	v_mfma_f32_32x32x16_bf16 v[18:33], v[94:97], v[86:89], v[18:33]
	ds_read_b128 v[194:197], v243 offset:32768
	v_mfma_f32_32x32x16_bf16 v[2:17], v[94:97], v[90:93], v[2:17]
	s_add_u32 m0, vcc_lo, 0x7000
	ds_read_b128 v[198:201], v243 offset:36864
	global_load_lds_dwordx4 v213, s[38:39]
	v_mfma_f32_32x32x16_bf16 v[34:49], v[82:85], v[90:93], v[34:49]
	ds_read_b128 v[202:205], v239 offset:36864
	s_add_u32 s36, s36, 0x80
	s_addc_u32 s37, s37, 0
	s_add_u32 s38, s38, 0x80
	s_addc_u32 s39, s39, 0
	s_waitcnt vmcnt(0) lgkmcnt(0)
	s_barrier
	v_mfma_f32_32x32x16_bf16 v[50:65], v[168:171], v[172:175], v[50:65]
	s_add_u32 m0, vcc_lo, 0x8000
	ds_read_b128 v[66:69], v236
	global_load_lds_dwordx4 v206, s[36:37]
	s_setprio 3
	v_mfma_f32_32x32x16_bf16 v[18:33], v[180:183], v[172:175], v[18:33]
	ds_read_b128 v[70:73], v240
	v_mfma_f32_32x32x16_bf16 v[2:17], v[180:183], v[176:179], v[2:17]
	s_add_u32 m0, vcc_lo, 0x9000
	ds_read_b128 v[74:77], v240 offset:4096
	global_load_lds_dwordx4 v207, s[36:37]
	v_mfma_f32_32x32x16_bf16 v[34:49], v[168:171], v[176:179], v[34:49]
	ds_read_b128 v[78:81], v236 offset:4096
	v_mfma_f32_32x32x16_bf16 v[50:65], v[190:193], v[194:197], v[50:65]
	s_add_u32 m0, vcc_lo, 0xa000
	ds_read_b128 v[82:85], v237
	global_load_lds_dwordx4 v208, s[36:37]
	v_mfma_f32_32x32x16_bf16 v[18:33], v[202:205], v[194:197], v[18:33]
	ds_read_b128 v[86:89], v241
	v_mfma_f32_32x32x16_bf16 v[2:17], v[202:205], v[198:201], v[2:17]
	s_add_u32 m0, vcc_lo, 0xb000
	ds_read_b128 v[90:93], v241 offset:4096
	global_load_lds_dwordx4 v209, s[36:37]
	v_mfma_f32_32x32x16_bf16 v[34:49], v[190:193], v[198:201], v[34:49]
	ds_read_b128 v[94:97], v237 offset:4096
	s_waitcnt lgkmcnt(6)
	v_mfma_f32_32x32x16_bf16 v[50:65], v[66:69], v[70:73], v[50:65]
	s_add_u32 m0, vcc_lo, 0xc000
	ds_read_b128 v[168:171], v238
	global_load_lds_dwordx4 v210, s[38:39]
	s_waitcnt lgkmcnt(5)
	v_mfma_f32_32x32x16_bf16 v[18:33], v[78:81], v[70:73], v[18:33]
	ds_read_b128 v[172:175], v242
	v_mfma_f32_32x32x16_bf16 v[2:17], v[78:81], v[74:77], v[2:17]
	s_add_u32 m0, vcc_lo, 0xd000
	ds_read_b128 v[176:179], v242 offset:4096
	global_load_lds_dwordx4 v211, s[38:39]
	v_mfma_f32_32x32x16_bf16 v[34:49], v[66:69], v[74:77], v[34:49]
	ds_read_b128 v[180:183], v238 offset:4096
	s_waitcnt lgkmcnt(6)
	v_mfma_f32_32x32x16_bf16 v[50:65], v[82:85], v[86:89], v[50:65]
	s_add_u32 m0, vcc_lo, 0xe000
	ds_read_b128 v[190:193], v239
	global_load_lds_dwordx4 v212, s[38:39]
	s_waitcnt lgkmcnt(5)
	v_mfma_f32_32x32x16_bf16 v[18:33], v[94:97], v[86:89], v[18:33]
	ds_read_b128 v[194:197], v243
	v_mfma_f32_32x32x16_bf16 v[2:17], v[94:97], v[90:93], v[2:17]
	s_add_u32 m0, vcc_lo, 0xf000
	ds_read_b128 v[198:201], v243 offset:4096
	global_load_lds_dwordx4 v213, s[38:39]
	v_mfma_f32_32x32x16_bf16 v[34:49], v[82:85], v[90:93], v[34:49]
	ds_read_b128 v[202:205], v239 offset:4096
	s_add_u32 s36, s36, 0x80
	s_addc_u32 s37, s37, 0
	s_add_u32 s38, s38, 0x80
	s_addc_u32 s39, s39, 0
	s_waitcnt vmcnt(0) lgkmcnt(0)
	s_barrier
	v_mfma_f32_32x32x16_bf16 v[50:65], v[168:171], v[172:175], v[50:65]
	s_mov_b32 m0, vcc_lo
	ds_read_b128 v[66:69], v236 offset:32768
	global_load_lds_dwordx4 v206, s[36:37]
	s_setprio 3
	v_mfma_f32_32x32x16_bf16 v[18:33], v[180:183], v[172:175], v[18:33]
	ds_read_b128 v[70:73], v240 offset:32768
	v_mfma_f32_32x32x16_bf16 v[2:17], v[180:183], v[176:179], v[2:17]
	s_add_u32 m0, vcc_lo, 0x1000
	ds_read_b128 v[74:77], v240 offset:36864
	global_load_lds_dwordx4 v207, s[36:37]
	v_mfma_f32_32x32x16_bf16 v[34:49], v[168:171], v[176:179], v[34:49]
	ds_read_b128 v[78:81], v236 offset:36864
	v_mfma_f32_32x32x16_bf16 v[50:65], v[190:193], v[194:197], v[50:65]
	s_add_u32 m0, vcc_lo, 0x2000
	ds_read_b128 v[82:85], v237 offset:32768
	global_load_lds_dwordx4 v208, s[36:37]
	v_mfma_f32_32x32x16_bf16 v[18:33], v[202:205], v[194:197], v[18:33]
	ds_read_b128 v[86:89], v241 offset:32768
	v_mfma_f32_32x32x16_bf16 v[2:17], v[202:205], v[198:201], v[2:17]
	s_add_u32 m0, vcc_lo, 0x3000
	ds_read_b128 v[90:93], v241 offset:36864
	global_load_lds_dwordx4 v209, s[36:37]
	v_mfma_f32_32x32x16_bf16 v[34:49], v[190:193], v[198:201], v[34:49]
	ds_read_b128 v[94:97], v237 offset:36864
	s_waitcnt lgkmcnt(6)
	v_mfma_f32_32x32x16_bf16 v[50:65], v[66:69], v[70:73], v[50:65]
	s_add_u32 m0, vcc_lo, 0x4000
	ds_read_b128 v[168:171], v238 offset:32768
	global_load_lds_dwordx4 v210, s[38:39]
	s_waitcnt lgkmcnt(5)
	v_mfma_f32_32x32x16_bf16 v[18:33], v[78:81], v[70:73], v[18:33]
	ds_read_b128 v[172:175], v242 offset:32768
	v_mfma_f32_32x32x16_bf16 v[2:17], v[78:81], v[74:77], v[2:17]
	s_add_u32 m0, vcc_lo, 0x5000
	ds_read_b128 v[176:179], v242 offset:36864
	global_load_lds_dwordx4 v211, s[38:39]
	v_mfma_f32_32x32x16_bf16 v[34:49], v[66:69], v[74:77], v[34:49]
	ds_read_b128 v[180:183], v238 offset:36864
	s_waitcnt lgkmcnt(6)
	v_mfma_f32_32x32x16_bf16 v[50:65], v[82:85], v[86:89], v[50:65]
	s_add_u32 m0, vcc_lo, 0x6000
	ds_read_b128 v[190:193], v239 offset:32768
	global_load_lds_dwordx4 v212, s[38:39]
	s_waitcnt lgkmcnt(5)
	v_mfma_f32_32x32x16_bf16 v[18:33], v[94:97], v[86:89], v[18:33]
	ds_read_b128 v[194:197], v243 offset:32768
	v_mfma_f32_32x32x16_bf16 v[2:17], v[94:97], v[90:93], v[2:17]
	s_add_u32 m0, vcc_lo, 0x7000
	ds_read_b128 v[198:201], v243 offset:36864
	global_load_lds_dwordx4 v213, s[38:39]
	v_mfma_f32_32x32x16_bf16 v[34:49], v[82:85], v[90:93], v[34:49]
	ds_read_b128 v[202:205], v239 offset:36864
	s_add_u32 s36, s36, 0x80
	s_addc_u32 s37, s37, 0
	s_add_u32 s38, s38, 0x80
	s_addc_u32 s39, s39, 0
	s_waitcnt vmcnt(0) lgkmcnt(0)
	s_barrier
	v_mfma_f32_32x32x16_bf16 v[50:65], v[168:171], v[172:175], v[50:65]
	s_add_u32 m0, vcc_lo, 0x8000
	ds_read_b128 v[66:69], v236
	global_load_lds_dwordx4 v206, s[36:37]
	s_setprio 3
	v_mfma_f32_32x32x16_bf16 v[18:33], v[180:183], v[172:175], v[18:33]
	ds_read_b128 v[70:73], v240
	v_mfma_f32_32x32x16_bf16 v[2:17], v[180:183], v[176:179], v[2:17]
	s_add_u32 m0, vcc_lo, 0x9000
	ds_read_b128 v[74:77], v240 offset:4096
	global_load_lds_dwordx4 v207, s[36:37]
	v_mfma_f32_32x32x16_bf16 v[34:49], v[168:171], v[176:179], v[34:49]
	ds_read_b128 v[78:81], v236 offset:4096
	v_mfma_f32_32x32x16_bf16 v[50:65], v[190:193], v[194:197], v[50:65]
	s_add_u32 m0, vcc_lo, 0xa000
	ds_read_b128 v[82:85], v237
	global_load_lds_dwordx4 v208, s[36:37]
	v_mfma_f32_32x32x16_bf16 v[18:33], v[202:205], v[194:197], v[18:33]
	ds_read_b128 v[86:89], v241
	v_mfma_f32_32x32x16_bf16 v[2:17], v[202:205], v[198:201], v[2:17]
	s_add_u32 m0, vcc_lo, 0xb000
	ds_read_b128 v[90:93], v241 offset:4096
	global_load_lds_dwordx4 v209, s[36:37]
	v_mfma_f32_32x32x16_bf16 v[34:49], v[190:193], v[198:201], v[34:49]
	ds_read_b128 v[94:97], v237 offset:4096
	s_waitcnt lgkmcnt(6)
	v_mfma_f32_32x32x16_bf16 v[50:65], v[66:69], v[70:73], v[50:65]
	s_add_u32 m0, vcc_lo, 0xc000
	ds_read_b128 v[168:171], v238
	global_load_lds_dwordx4 v210, s[38:39]
	s_waitcnt lgkmcnt(5)
	v_mfma_f32_32x32x16_bf16 v[18:33], v[78:81], v[70:73], v[18:33]
	ds_read_b128 v[172:175], v242
	v_mfma_f32_32x32x16_bf16 v[2:17], v[78:81], v[74:77], v[2:17]
	s_add_u32 m0, vcc_lo, 0xd000
	ds_read_b128 v[176:179], v242 offset:4096
	global_load_lds_dwordx4 v211, s[38:39]
	v_mfma_f32_32x32x16_bf16 v[34:49], v[66:69], v[74:77], v[34:49]
	ds_read_b128 v[180:183], v238 offset:4096
	s_waitcnt lgkmcnt(6)
	v_mfma_f32_32x32x16_bf16 v[50:65], v[82:85], v[86:89], v[50:65]
	s_add_u32 m0, vcc_lo, 0xe000
	ds_read_b128 v[190:193], v239
	global_load_lds_dwordx4 v212, s[38:39]
	s_waitcnt lgkmcnt(5)
	v_mfma_f32_32x32x16_bf16 v[18:33], v[94:97], v[86:89], v[18:33]
	ds_read_b128 v[194:197], v243
	v_mfma_f32_32x32x16_bf16 v[2:17], v[94:97], v[90:93], v[2:17]
	s_add_u32 m0, vcc_lo, 0xf000
	ds_read_b128 v[198:201], v243 offset:4096
	global_load_lds_dwordx4 v213, s[38:39]
	v_mfma_f32_32x32x16_bf16 v[34:49], v[82:85], v[90:93], v[34:49]
	ds_read_b128 v[202:205], v239 offset:4096
	s_add_u32 s38, s38, 0x80
	s_addc_u32 s39, s39, 0
	s_add_u32 s36, s50, 0x5c25000
	s_addc_u32 s37, s51, 0
	s_waitcnt vmcnt(0) lgkmcnt(0)
	s_barrier
	v_mfma_f32_32x32x16_bf16 v[50:65], v[168:171], v[172:175], v[50:65]
	s_mov_b32 m0, vcc_lo
	ds_read_b128 v[66:69], v236 offset:32768
	global_load_lds_dwordx4 v222, s[40:41]
	s_setprio 3
	v_mfma_f32_32x32x16_bf16 v[18:33], v[180:183], v[172:175], v[18:33]
	ds_read_b128 v[70:73], v240 offset:32768
	v_mfma_f32_32x32x16_bf16 v[2:17], v[180:183], v[176:179], v[2:17]
	s_add_u32 m0, vcc_lo, 0x1000
	ds_read_b128 v[74:77], v240 offset:36864
	global_load_lds_dwordx4 v223, s[40:41]
	v_mfma_f32_32x32x16_bf16 v[34:49], v[168:171], v[176:179], v[34:49]
	ds_read_b128 v[78:81], v236 offset:36864
	v_mfma_f32_32x32x16_bf16 v[50:65], v[190:193], v[194:197], v[50:65]
	s_add_u32 m0, vcc_lo, 0x2000
	ds_read_b128 v[82:85], v237 offset:32768
	global_load_lds_dwordx4 v224, s[40:41]
	v_mfma_f32_32x32x16_bf16 v[18:33], v[202:205], v[194:197], v[18:33]
	ds_read_b128 v[86:89], v241 offset:32768
	v_mfma_f32_32x32x16_bf16 v[2:17], v[202:205], v[198:201], v[2:17]
	s_add_u32 m0, vcc_lo, 0x3000
	ds_read_b128 v[90:93], v241 offset:36864
	global_load_lds_dwordx4 v225, s[40:41]
	v_mfma_f32_32x32x16_bf16 v[34:49], v[190:193], v[198:201], v[34:49]
	ds_read_b128 v[94:97], v237 offset:36864
	s_waitcnt lgkmcnt(6)
	v_mfma_f32_32x32x16_bf16 v[50:65], v[66:69], v[70:73], v[50:65]
	s_add_u32 m0, vcc_lo, 0x4000
	ds_read_b128 v[168:171], v238 offset:32768
	global_load_lds_dwordx4 v222, s[42:43]
	s_waitcnt lgkmcnt(5)
	v_mfma_f32_32x32x16_bf16 v[18:33], v[78:81], v[70:73], v[18:33]
	ds_read_b128 v[172:175], v242 offset:32768
	v_mfma_f32_32x32x16_bf16 v[2:17], v[78:81], v[74:77], v[2:17]
	s_add_u32 m0, vcc_lo, 0x5000
	ds_read_b128 v[176:179], v242 offset:36864
	global_load_lds_dwordx4 v223, s[42:43]
	v_mfma_f32_32x32x16_bf16 v[34:49], v[66:69], v[74:77], v[34:49]
	ds_read_b128 v[180:183], v238 offset:36864
	s_waitcnt lgkmcnt(6)
	v_mfma_f32_32x32x16_bf16 v[50:65], v[82:85], v[86:89], v[50:65]
	s_add_u32 m0, vcc_lo, 0x6000
	ds_read_b128 v[190:193], v239 offset:32768
	global_load_lds_dwordx4 v224, s[42:43]
	s_waitcnt lgkmcnt(5)
	v_mfma_f32_32x32x16_bf16 v[18:33], v[94:97], v[86:89], v[18:33]
	ds_read_b128 v[194:197], v243 offset:32768
	v_mfma_f32_32x32x16_bf16 v[2:17], v[94:97], v[90:93], v[2:17]
	s_add_u32 m0, vcc_lo, 0x7000
	ds_read_b128 v[198:201], v243 offset:36864
	global_load_lds_dwordx4 v225, s[42:43]
	v_mfma_f32_32x32x16_bf16 v[34:49], v[82:85], v[90:93], v[34:49]
	ds_read_b128 v[202:205], v239 offset:36864
	s_add_u32 s40, s40, 0x800
	s_addc_u32 s41, s41, 0
	s_add_u32 s42, s42, 0x800
	s_addc_u32 s43, s43, 0
	s_waitcnt vmcnt(0) lgkmcnt(0)
	s_barrier
	s_add_u32 m0, vcc_lo, 0x8000
	v_mfma_f32_32x32x16_bf16 v[50:65], v[168:171], v[172:175], v[50:65]
	global_load_lds_dwordx4 v206, s[36:37]
	s_add_u32 m0, vcc_lo, 0x9000
	v_mfma_f32_32x32x16_bf16 v[18:33], v[180:183], v[172:175], v[18:33]
	global_load_lds_dwordx4 v207, s[36:37]
	s_add_u32 m0, vcc_lo, 0xa000
	v_mfma_f32_32x32x16_bf16 v[2:17], v[180:183], v[176:179], v[2:17]
	global_load_lds_dwordx4 v208, s[36:37]
	s_add_u32 m0, vcc_lo, 0xb000
	v_mfma_f32_32x32x16_bf16 v[34:49], v[168:171], v[176:179], v[34:49]
	global_load_lds_dwordx4 v209, s[36:37]
	s_add_u32 m0, vcc_lo, 0xc000
	v_mfma_f32_32x32x16_bf16 v[50:65], v[190:193], v[194:197], v[50:65]
	global_load_lds_dwordx4 v210, s[38:39]
	s_add_u32 m0, vcc_lo, 0xd000
	v_mfma_f32_32x32x16_bf16 v[18:33], v[202:205], v[194:197], v[18:33]
	global_load_lds_dwordx4 v211, s[38:39]
	s_add_u32 m0, vcc_lo, 0xe000
	v_mfma_f32_32x32x16_bf16 v[2:17], v[202:205], v[198:201], v[2:17]
	global_load_lds_dwordx4 v212, s[38:39]
	s_add_u32 m0, vcc_lo, 0xf000
	v_mfma_f32_32x32x16_bf16 v[34:49], v[190:193], v[198:201], v[34:49]
	global_load_lds_dwordx4 v213, s[38:39]
	s_add_u32 s36, s36, 0x80
	s_addc_u32 s37, s37, 0
	s_add_u32 s38, s38, 0x80
	s_addc_u32 s39, s39, 0
	s_setprio 0
	ds_read_u16 v66, v244 offset:0
	ds_read_u16 v67, v244 offset:128
	ds_read_u16 v68, v245 offset:256
	ds_read_u16 v69, v245 offset:384
	ds_read_u16 v70, v244 offset:1088
	ds_read_u16 v71, v244 offset:1216
	ds_read_u16 v72, v245 offset:1344
	ds_read_u16 v73, v245 offset:1472
	s_nop 7
	s_nop 7
	ds_read_u16 v74, v244 offset:2048
	ds_read_u16 v75, v244 offset:2176
	ds_read_u16 v76, v245 offset:2304
	ds_read_u16 v77, v245 offset:2432
	ds_read_u16 v78, v244 offset:3136
	ds_read_u16 v79, v244 offset:3264
	ds_read_u16 v80, v245 offset:3392
	ds_read_u16 v81, v245 offset:3520
	s_waitcnt lgkmcnt(8)
	v_lshlrev_b32_e32 v66, 16, v66
	v_lshlrev_b32_e32 v67, 16, v67
	v_lshlrev_b32_e32 v68, 16, v68
	v_lshlrev_b32_e32 v69, 16, v69
	v_mul_f32_e32 v66, 0xbfb8aa3b, v66
	v_mul_f32_e32 v67, 0xbfb8aa3b, v67
	v_mul_f32_e32 v68, 0xbfb8aa3b, v68
	v_mul_f32_e32 v69, 0xbfb8aa3b, v69
	v_exp_f32_e32 v66, v66
	v_exp_f32_e32 v67, v67
	v_exp_f32_e32 v68, v68
	v_exp_f32_e32 v69, v69
	v_add_f32_e32 v66, 1.0, v66
	v_add_f32_e32 v67, 1.0, v67
	v_add_f32_e32 v68, 1.0, v68
	v_add_f32_e32 v69, 1.0, v69
	v_rcp_f32_e32 v66, v66
	v_rcp_f32_e32 v67, v67
	v_rcp_f32_e32 v68, v68
	v_rcp_f32_e32 v69, v69
	s_nop 0
	v_pk_fma_f32 v[166:167], v[50:51], v[66:67], v[166:167]
	v_pk_fma_f32 v[164:165], v[52:53], v[68:69], v[164:165]
	v_lshlrev_b32_e32 v70, 16, v70
	v_lshlrev_b32_e32 v71, 16, v71
	v_lshlrev_b32_e32 v72, 16, v72
	v_lshlrev_b32_e32 v73, 16, v73
	v_mul_f32_e32 v70, 0xbfb8aa3b, v70
	v_mul_f32_e32 v71, 0xbfb8aa3b, v71
	v_mul_f32_e32 v72, 0xbfb8aa3b, v72
	v_mul_f32_e32 v73, 0xbfb8aa3b, v73
	v_exp_f32_e32 v70, v70
	v_exp_f32_e32 v71, v71
	v_exp_f32_e32 v72, v72
	v_exp_f32_e32 v73, v73
	v_add_f32_e32 v70, 1.0, v70
	v_add_f32_e32 v71, 1.0, v71
	v_add_f32_e32 v72, 1.0, v72
	v_add_f32_e32 v73, 1.0, v73
	v_rcp_f32_e32 v70, v70
	v_rcp_f32_e32 v71, v71
	v_rcp_f32_e32 v72, v72
	v_rcp_f32_e32 v73, v73
	s_nop 0
	v_pk_fma_f32 v[162:163], v[54:55], v[70:71], v[162:163]
	v_pk_fma_f32 v[160:161], v[56:57], v[72:73], v[160:161]
	ds_read_u16 v82, v244 offset:4096
	ds_read_u16 v83, v244 offset:4224
	ds_read_u16 v84, v245 offset:4352
	ds_read_u16 v85, v245 offset:4480
	ds_read_u16 v86, v244 offset:5184
	ds_read_u16 v87, v244 offset:5312
	ds_read_u16 v88, v245 offset:5440
	ds_read_u16 v89, v245 offset:5568
	s_waitcnt lgkmcnt(8)
	v_lshlrev_b32_e32 v74, 16, v74
	v_lshlrev_b32_e32 v75, 16, v75
	v_lshlrev_b32_e32 v76, 16, v76
	v_lshlrev_b32_e32 v77, 16, v77
	v_mul_f32_e32 v74, 0xbfb8aa3b, v74
	v_mul_f32_e32 v75, 0xbfb8aa3b, v75
	v_mul_f32_e32 v76, 0xbfb8aa3b, v76
	v_mul_f32_e32 v77, 0xbfb8aa3b, v77
	v_exp_f32_e32 v74, v74
	v_exp_f32_e32 v75, v75
	v_exp_f32_e32 v76, v76
	v_exp_f32_e32 v77, v77
	v_add_f32_e32 v74, 1.0, v74
	v_add_f32_e32 v75, 1.0, v75
	v_add_f32_e32 v76, 1.0, v76
	v_add_f32_e32 v77, 1.0, v77
	v_rcp_f32_e32 v74, v74
	v_rcp_f32_e32 v75, v75
	v_rcp_f32_e32 v76, v76
	v_rcp_f32_e32 v77, v77
	s_nop 0
	v_pk_fma_f32 v[158:159], v[58:59], v[74:75], v[158:159]
	v_pk_fma_f32 v[156:157], v[60:61], v[76:77], v[156:157]
	v_lshlrev_b32_e32 v78, 16, v78
	v_lshlrev_b32_e32 v79, 16, v79
	v_lshlrev_b32_e32 v80, 16, v80
	v_lshlrev_b32_e32 v81, 16, v81
	v_mul_f32_e32 v78, 0xbfb8aa3b, v78
	v_mul_f32_e32 v79, 0xbfb8aa3b, v79
	v_mul_f32_e32 v80, 0xbfb8aa3b, v80
	v_mul_f32_e32 v81, 0xbfb8aa3b, v81
	v_exp_f32_e32 v78, v78
	v_exp_f32_e32 v79, v79
	v_exp_f32_e32 v80, v80
	v_exp_f32_e32 v81, v81
	v_add_f32_e32 v78, 1.0, v78
	v_add_f32_e32 v79, 1.0, v79
	v_add_f32_e32 v80, 1.0, v80
	v_add_f32_e32 v81, 1.0, v81
	v_rcp_f32_e32 v78, v78
	v_rcp_f32_e32 v79, v79
	v_rcp_f32_e32 v80, v80
	v_rcp_f32_e32 v81, v81
	s_nop 0
	v_pk_fma_f32 v[154:155], v[62:63], v[78:79], v[154:155]
	v_pk_fma_f32 v[152:153], v[64:65], v[80:81], v[152:153]
	ds_read_u16 v90, v244 offset:6144
	ds_read_u16 v91, v244 offset:6272
	ds_read_u16 v92, v245 offset:6400
	ds_read_u16 v93, v245 offset:6528
	ds_read_u16 v94, v244 offset:7232
	ds_read_u16 v95, v244 offset:7360
	ds_read_u16 v96, v245 offset:7488
	ds_read_u16 v97, v245 offset:7616
	s_waitcnt lgkmcnt(8)
	v_lshlrev_b32_e32 v82, 16, v82
	v_lshlrev_b32_e32 v83, 16, v83
	v_lshlrev_b32_e32 v84, 16, v84
	v_lshlrev_b32_e32 v85, 16, v85
	v_mul_f32_e32 v82, 0xbfb8aa3b, v82
	v_mul_f32_e32 v83, 0xbfb8aa3b, v83
	v_mul_f32_e32 v84, 0xbfb8aa3b, v84
	v_mul_f32_e32 v85, 0xbfb8aa3b, v85
	v_exp_f32_e32 v82, v82
	v_exp_f32_e32 v83, v83
	v_exp_f32_e32 v84, v84
	v_exp_f32_e32 v85, v85
	v_add_f32_e32 v82, 1.0, v82
	v_add_f32_e32 v83, 1.0, v83
	v_add_f32_e32 v84, 1.0, v84
	v_add_f32_e32 v85, 1.0, v85
	v_rcp_f32_e32 v82, v82
	v_rcp_f32_e32 v83, v83
	v_rcp_f32_e32 v84, v84
	v_rcp_f32_e32 v85, v85
	s_nop 0
	v_pk_fma_f32 v[130:131], v[18:19], v[82:83], v[130:131]
	v_pk_fma_f32 v[128:129], v[20:21], v[84:85], v[128:129]
	v_lshlrev_b32_e32 v86, 16, v86
	v_lshlrev_b32_e32 v87, 16, v87
	v_lshlrev_b32_e32 v88, 16, v88
	v_lshlrev_b32_e32 v89, 16, v89
	v_mul_f32_e32 v86, 0xbfb8aa3b, v86
	v_mul_f32_e32 v87, 0xbfb8aa3b, v87
	v_mul_f32_e32 v88, 0xbfb8aa3b, v88
	v_mul_f32_e32 v89, 0xbfb8aa3b, v89
	v_exp_f32_e32 v86, v86
	v_exp_f32_e32 v87, v87
	v_exp_f32_e32 v88, v88
	v_exp_f32_e32 v89, v89
	v_add_f32_e32 v86, 1.0, v86
	v_add_f32_e32 v87, 1.0, v87
	v_add_f32_e32 v88, 1.0, v88
	v_add_f32_e32 v89, 1.0, v89
	v_rcp_f32_e32 v86, v86
	v_rcp_f32_e32 v87, v87
	v_rcp_f32_e32 v88, v88
	v_rcp_f32_e32 v89, v89
	s_nop 0
	v_pk_fma_f32 v[126:127], v[22:23], v[86:87], v[126:127]
	v_pk_fma_f32 v[124:125], v[24:25], v[88:89], v[124:125]
	ds_read_u16 v168, v244 offset:4160
	ds_read_u16 v169, v244 offset:4288
	ds_read_u16 v170, v245 offset:4416
	ds_read_u16 v171, v245 offset:4544
	ds_read_u16 v172, v244 offset:5120
	ds_read_u16 v173, v244 offset:5248
	ds_read_u16 v174, v245 offset:5376
	ds_read_u16 v175, v245 offset:5504
	s_waitcnt lgkmcnt(8)
	v_lshlrev_b32_e32 v90, 16, v90
	v_lshlrev_b32_e32 v91, 16, v91
	v_lshlrev_b32_e32 v92, 16, v92
	v_lshlrev_b32_e32 v93, 16, v93
	v_mul_f32_e32 v90, 0xbfb8aa3b, v90
	v_mul_f32_e32 v91, 0xbfb8aa3b, v91
	v_mul_f32_e32 v92, 0xbfb8aa3b, v92
	v_mul_f32_e32 v93, 0xbfb8aa3b, v93
	v_exp_f32_e32 v90, v90
	v_exp_f32_e32 v91, v91
	v_exp_f32_e32 v92, v92
	v_exp_f32_e32 v93, v93
	v_add_f32_e32 v90, 1.0, v90
	v_add_f32_e32 v91, 1.0, v91
	v_add_f32_e32 v92, 1.0, v92
	v_add_f32_e32 v93, 1.0, v93
	v_rcp_f32_e32 v90, v90
	v_rcp_f32_e32 v91, v91
	v_rcp_f32_e32 v92, v92
	v_rcp_f32_e32 v93, v93
	s_nop 0
	v_pk_fma_f32 v[122:123], v[26:27], v[90:91], v[122:123]
	v_pk_fma_f32 v[120:121], v[28:29], v[92:93], v[120:121]
	v_lshlrev_b32_e32 v94, 16, v94
	v_lshlrev_b32_e32 v95, 16, v95
	v_lshlrev_b32_e32 v96, 16, v96
	v_lshlrev_b32_e32 v97, 16, v97
	v_mul_f32_e32 v94, 0xbfb8aa3b, v94
	v_mul_f32_e32 v95, 0xbfb8aa3b, v95
	v_mul_f32_e32 v96, 0xbfb8aa3b, v96
	v_mul_f32_e32 v97, 0xbfb8aa3b, v97
	v_exp_f32_e32 v94, v94
	v_exp_f32_e32 v95, v95
	v_exp_f32_e32 v96, v96
	v_exp_f32_e32 v97, v97
	v_add_f32_e32 v94, 1.0, v94
	v_add_f32_e32 v95, 1.0, v95
	v_add_f32_e32 v96, 1.0, v96
	v_add_f32_e32 v97, 1.0, v97
	v_rcp_f32_e32 v94, v94
	v_rcp_f32_e32 v95, v95
	v_rcp_f32_e32 v96, v96
	v_rcp_f32_e32 v97, v97
	s_nop 0
	v_pk_fma_f32 v[118:119], v[30:31], v[94:95], v[118:119]
	v_pk_fma_f32 v[116:117], v[32:33], v[96:97], v[116:117]
	ds_read_u16 v176, v244 offset:6208
	ds_read_u16 v177, v244 offset:6336
	ds_read_u16 v178, v245 offset:6464
	ds_read_u16 v179, v245 offset:6592
	ds_read_u16 v180, v244 offset:7168
	ds_read_u16 v181, v244 offset:7296
	ds_read_u16 v182, v245 offset:7424
	ds_read_u16 v183, v245 offset:7552
	s_waitcnt lgkmcnt(8)
	v_lshlrev_b32_e32 v168, 16, v168
	v_lshlrev_b32_e32 v169, 16, v169
	v_lshlrev_b32_e32 v170, 16, v170
	v_lshlrev_b32_e32 v171, 16, v171
	v_mul_f32_e32 v168, 0xbfb8aa3b, v168
	v_mul_f32_e32 v169, 0xbfb8aa3b, v169
	v_mul_f32_e32 v170, 0xbfb8aa3b, v170
	v_mul_f32_e32 v171, 0xbfb8aa3b, v171
	v_exp_f32_e32 v168, v168
	v_exp_f32_e32 v169, v169
	v_exp_f32_e32 v170, v170
	v_exp_f32_e32 v171, v171
	v_add_f32_e32 v168, 1.0, v168
	v_add_f32_e32 v169, 1.0, v169
	v_add_f32_e32 v170, 1.0, v170
	v_add_f32_e32 v171, 1.0, v171
	v_rcp_f32_e32 v168, v168
	v_rcp_f32_e32 v169, v169
	v_rcp_f32_e32 v170, v170
	v_rcp_f32_e32 v171, v171
	s_nop 0
	v_pk_fma_f32 v[114:115], v[2:3], v[168:169], v[114:115]
	v_pk_fma_f32 v[112:113], v[4:5], v[170:171], v[112:113]
	v_lshlrev_b32_e32 v172, 16, v172
	v_lshlrev_b32_e32 v173, 16, v173
	v_lshlrev_b32_e32 v174, 16, v174
	v_lshlrev_b32_e32 v175, 16, v175
	v_mul_f32_e32 v172, 0xbfb8aa3b, v172
	v_mul_f32_e32 v173, 0xbfb8aa3b, v173
	v_mul_f32_e32 v174, 0xbfb8aa3b, v174
	v_mul_f32_e32 v175, 0xbfb8aa3b, v175
	v_exp_f32_e32 v172, v172
	v_exp_f32_e32 v173, v173
	v_exp_f32_e32 v174, v174
	v_exp_f32_e32 v175, v175
	v_add_f32_e32 v172, 1.0, v172
	v_add_f32_e32 v173, 1.0, v173
	v_add_f32_e32 v174, 1.0, v174
	v_add_f32_e32 v175, 1.0, v175
	v_rcp_f32_e32 v172, v172
	v_rcp_f32_e32 v173, v173
	v_rcp_f32_e32 v174, v174
	v_rcp_f32_e32 v175, v175
	s_nop 0
	v_pk_fma_f32 v[110:111], v[6:7], v[172:173], v[110:111]
	v_pk_fma_f32 v[108:109], v[8:9], v[174:175], v[108:109]
	ds_read_u16 v190, v244 offset:64
	ds_read_u16 v191, v244 offset:192
	ds_read_u16 v192, v245 offset:320
	ds_read_u16 v193, v245 offset:448
	ds_read_u16 v194, v244 offset:1024
	ds_read_u16 v195, v244 offset:1152
	ds_read_u16 v196, v245 offset:1280
	ds_read_u16 v197, v245 offset:1408
	s_waitcnt lgkmcnt(8)
	v_lshlrev_b32_e32 v176, 16, v176
	v_lshlrev_b32_e32 v177, 16, v177
	v_lshlrev_b32_e32 v178, 16, v178
	v_lshlrev_b32_e32 v179, 16, v179
	v_mul_f32_e32 v176, 0xbfb8aa3b, v176
	v_mul_f32_e32 v177, 0xbfb8aa3b, v177
	v_mul_f32_e32 v178, 0xbfb8aa3b, v178
	v_mul_f32_e32 v179, 0xbfb8aa3b, v179
	v_exp_f32_e32 v176, v176
	v_exp_f32_e32 v177, v177
	v_exp_f32_e32 v178, v178
	v_exp_f32_e32 v179, v179
	v_add_f32_e32 v176, 1.0, v176
	v_add_f32_e32 v177, 1.0, v177
	v_add_f32_e32 v178, 1.0, v178
	v_add_f32_e32 v179, 1.0, v179
	v_rcp_f32_e32 v176, v176
	v_rcp_f32_e32 v177, v177
	v_rcp_f32_e32 v178, v178
	v_rcp_f32_e32 v179, v179
	s_nop 0
	v_pk_fma_f32 v[106:107], v[10:11], v[176:177], v[106:107]
	v_pk_fma_f32 v[104:105], v[12:13], v[178:179], v[104:105]
	v_lshlrev_b32_e32 v180, 16, v180
	v_lshlrev_b32_e32 v181, 16, v181
	v_lshlrev_b32_e32 v182, 16, v182
	v_lshlrev_b32_e32 v183, 16, v183
	v_mul_f32_e32 v180, 0xbfb8aa3b, v180
	v_mul_f32_e32 v181, 0xbfb8aa3b, v181
	v_mul_f32_e32 v182, 0xbfb8aa3b, v182
	v_mul_f32_e32 v183, 0xbfb8aa3b, v183
	v_exp_f32_e32 v180, v180
	v_exp_f32_e32 v181, v181
	v_exp_f32_e32 v182, v182
	v_exp_f32_e32 v183, v183
	v_add_f32_e32 v180, 1.0, v180
	v_add_f32_e32 v181, 1.0, v181
	v_add_f32_e32 v182, 1.0, v182
	v_add_f32_e32 v183, 1.0, v183
	v_rcp_f32_e32 v180, v180
	v_rcp_f32_e32 v181, v181
	v_rcp_f32_e32 v182, v182
	v_rcp_f32_e32 v183, v183
	s_nop 0
	v_pk_fma_f32 v[102:103], v[14:15], v[180:181], v[102:103]
	v_pk_fma_f32 v[100:101], v[16:17], v[182:183], v[100:101]
	ds_read_u16 v198, v244 offset:2112
	ds_read_u16 v199, v244 offset:2240
	ds_read_u16 v200, v245 offset:2368
	ds_read_u16 v201, v245 offset:2496
	ds_read_u16 v202, v244 offset:3072
	ds_read_u16 v203, v244 offset:3200
	ds_read_u16 v204, v245 offset:3328
	ds_read_u16 v205, v245 offset:3456
	s_waitcnt lgkmcnt(8)
	v_lshlrev_b32_e32 v190, 16, v190
	v_lshlrev_b32_e32 v191, 16, v191
	v_lshlrev_b32_e32 v192, 16, v192
	v_lshlrev_b32_e32 v193, 16, v193
	v_mul_f32_e32 v190, 0xbfb8aa3b, v190
	v_mul_f32_e32 v191, 0xbfb8aa3b, v191
	v_mul_f32_e32 v192, 0xbfb8aa3b, v192
	v_mul_f32_e32 v193, 0xbfb8aa3b, v193
	v_exp_f32_e32 v190, v190
	v_exp_f32_e32 v191, v191
	v_exp_f32_e32 v192, v192
	v_exp_f32_e32 v193, v193
	v_add_f32_e32 v190, 1.0, v190
	v_add_f32_e32 v191, 1.0, v191
	v_add_f32_e32 v192, 1.0, v192
	v_add_f32_e32 v193, 1.0, v193
	v_rcp_f32_e32 v190, v190
	v_rcp_f32_e32 v191, v191
	v_rcp_f32_e32 v192, v192
	v_rcp_f32_e32 v193, v193
	s_nop 0
	v_pk_fma_f32 v[150:151], v[34:35], v[190:191], v[150:151]
	v_pk_fma_f32 v[148:149], v[36:37], v[192:193], v[148:149]
	v_lshlrev_b32_e32 v194, 16, v194
	v_lshlrev_b32_e32 v195, 16, v195
	v_lshlrev_b32_e32 v196, 16, v196
	v_lshlrev_b32_e32 v197, 16, v197
	v_mul_f32_e32 v194, 0xbfb8aa3b, v194
	v_mul_f32_e32 v195, 0xbfb8aa3b, v195
	v_mul_f32_e32 v196, 0xbfb8aa3b, v196
	v_mul_f32_e32 v197, 0xbfb8aa3b, v197
	v_exp_f32_e32 v194, v194
	v_exp_f32_e32 v195, v195
	v_exp_f32_e32 v196, v196
	v_exp_f32_e32 v197, v197
	v_add_f32_e32 v194, 1.0, v194
	v_add_f32_e32 v195, 1.0, v195
	v_add_f32_e32 v196, 1.0, v196
	v_add_f32_e32 v197, 1.0, v197
	v_rcp_f32_e32 v194, v194
	v_rcp_f32_e32 v195, v195
	v_rcp_f32_e32 v196, v196
	v_rcp_f32_e32 v197, v197
	s_nop 0
	v_pk_fma_f32 v[146:147], v[38:39], v[194:195], v[146:147]
	v_pk_fma_f32 v[142:143], v[40:41], v[196:197], v[142:143]
	s_waitcnt lgkmcnt(0)
	v_lshlrev_b32_e32 v198, 16, v198
	v_lshlrev_b32_e32 v199, 16, v199
	v_lshlrev_b32_e32 v200, 16, v200
	v_lshlrev_b32_e32 v201, 16, v201
	v_mul_f32_e32 v198, 0xbfb8aa3b, v198
	v_mul_f32_e32 v199, 0xbfb8aa3b, v199
	v_mul_f32_e32 v200, 0xbfb8aa3b, v200
	v_mul_f32_e32 v201, 0xbfb8aa3b, v201
	v_exp_f32_e32 v198, v198
	v_exp_f32_e32 v199, v199
	v_exp_f32_e32 v200, v200
	v_exp_f32_e32 v201, v201
	v_add_f32_e32 v198, 1.0, v198
	v_add_f32_e32 v199, 1.0, v199
	v_add_f32_e32 v200, 1.0, v200
	v_add_f32_e32 v201, 1.0, v201
	v_rcp_f32_e32 v198, v198
	v_rcp_f32_e32 v199, v199
	v_rcp_f32_e32 v200, v200
	v_rcp_f32_e32 v201, v201
	s_nop 0
	v_pk_fma_f32 v[140:141], v[42:43], v[198:199], v[140:141]
	v_pk_fma_f32 v[138:139], v[44:45], v[200:201], v[138:139]
	v_lshlrev_b32_e32 v202, 16, v202
	v_lshlrev_b32_e32 v203, 16, v203
	v_lshlrev_b32_e32 v204, 16, v204
	v_lshlrev_b32_e32 v205, 16, v205
	v_mul_f32_e32 v202, 0xbfb8aa3b, v202
	v_mul_f32_e32 v203, 0xbfb8aa3b, v203
	v_mul_f32_e32 v204, 0xbfb8aa3b, v204
	v_mul_f32_e32 v205, 0xbfb8aa3b, v205
	v_exp_f32_e32 v202, v202
	v_exp_f32_e32 v203, v203
	v_exp_f32_e32 v204, v204
	v_exp_f32_e32 v205, v205
	v_add_f32_e32 v202, 1.0, v202
	v_add_f32_e32 v203, 1.0, v203
	v_add_f32_e32 v204, 1.0, v204
	v_add_f32_e32 v205, 1.0, v205
	v_rcp_f32_e32 v202, v202
	v_rcp_f32_e32 v203, v203
	v_rcp_f32_e32 v204, v204
	v_rcp_f32_e32 v205, v205
	s_nop 0
	v_pk_fma_f32 v[136:137], v[46:47], v[202:203], v[136:137]
	v_pk_fma_f32 v[134:135], v[48:49], v[204:205], v[134:135]
	s_waitcnt vmcnt(0) lgkmcnt(0)
	s_barrier
	s_mov_b32 m0, vcc_lo
	ds_read_b128 v[66:69], v236 offset:32768
	global_load_lds_dwordx4 v206, s[36:37]
	s_setprio 3
	ds_read_b128 v[70:73], v240 offset:32768
	s_add_u32 m0, vcc_lo, 0x1000
	ds_read_b128 v[74:77], v240 offset:36864
	global_load_lds_dwordx4 v207, s[36:37]
	ds_read_b128 v[78:81], v236 offset:36864
	s_add_u32 m0, vcc_lo, 0x2000
	ds_read_b128 v[82:85], v237 offset:32768
	global_load_lds_dwordx4 v208, s[36:37]
	ds_read_b128 v[86:89], v241 offset:32768
	s_add_u32 m0, vcc_lo, 0x3000
	ds_read_b128 v[90:93], v241 offset:36864
	global_load_lds_dwordx4 v209, s[36:37]
	ds_read_b128 v[94:97], v237 offset:36864
	s_waitcnt lgkmcnt(6)
	v_mfma_f32_32x32x16_bf16 v[50:65], v[66:69], v[70:73], 0
	s_add_u32 m0, vcc_lo, 0x4000
	ds_read_b128 v[168:171], v238 offset:32768
	global_load_lds_dwordx4 v210, s[38:39]
	s_waitcnt lgkmcnt(5)
	v_mfma_f32_32x32x16_bf16 v[18:33], v[78:81], v[70:73], 0
	ds_read_b128 v[172:175], v242 offset:32768
	v_mfma_f32_32x32x16_bf16 v[2:17], v[78:81], v[74:77], 0
	s_add_u32 m0, vcc_lo, 0x5000
	ds_read_b128 v[176:179], v242 offset:36864
	global_load_lds_dwordx4 v211, s[38:39]
	v_mfma_f32_32x32x16_bf16 v[34:49], v[66:69], v[74:77], 0
	ds_read_b128 v[180:183], v238 offset:36864
	s_waitcnt lgkmcnt(6)
	v_mfma_f32_32x32x16_bf16 v[50:65], v[82:85], v[86:89], v[50:65]
	s_add_u32 m0, vcc_lo, 0x6000
	ds_read_b128 v[190:193], v239 offset:32768
	global_load_lds_dwordx4 v212, s[38:39]
	s_waitcnt lgkmcnt(5)
	v_mfma_f32_32x32x16_bf16 v[18:33], v[94:97], v[86:89], v[18:33]
	ds_read_b128 v[194:197], v243 offset:32768
	v_mfma_f32_32x32x16_bf16 v[2:17], v[94:97], v[90:93], v[2:17]
	s_add_u32 m0, vcc_lo, 0x7000
	ds_read_b128 v[198:201], v243 offset:36864
	global_load_lds_dwordx4 v213, s[38:39]
	v_mfma_f32_32x32x16_bf16 v[34:49], v[82:85], v[90:93], v[34:49]
	ds_read_b128 v[202:205], v239 offset:36864
	s_add_u32 s36, s36, 0x80
	s_addc_u32 s37, s37, 0
	s_add_u32 s38, s38, 0x80
	s_addc_u32 s39, s39, 0
	s_waitcnt vmcnt(0) lgkmcnt(0)
	s_barrier
	v_mfma_f32_32x32x16_bf16 v[50:65], v[168:171], v[172:175], v[50:65]
	s_add_u32 m0, vcc_lo, 0x8000
	ds_read_b128 v[66:69], v236
	global_load_lds_dwordx4 v206, s[36:37]
	s_setprio 3
	v_mfma_f32_32x32x16_bf16 v[18:33], v[180:183], v[172:175], v[18:33]
	ds_read_b128 v[70:73], v240
	v_mfma_f32_32x32x16_bf16 v[2:17], v[180:183], v[176:179], v[2:17]
	s_add_u32 m0, vcc_lo, 0x9000
	ds_read_b128 v[74:77], v240 offset:4096
	global_load_lds_dwordx4 v207, s[36:37]
	v_mfma_f32_32x32x16_bf16 v[34:49], v[168:171], v[176:179], v[34:49]
	ds_read_b128 v[78:81], v236 offset:4096
	v_mfma_f32_32x32x16_bf16 v[50:65], v[190:193], v[194:197], v[50:65]
	s_add_u32 m0, vcc_lo, 0xa000
	ds_read_b128 v[82:85], v237
	global_load_lds_dwordx4 v208, s[36:37]
	v_mfma_f32_32x32x16_bf16 v[18:33], v[202:205], v[194:197], v[18:33]
	ds_read_b128 v[86:89], v241
	v_mfma_f32_32x32x16_bf16 v[2:17], v[202:205], v[198:201], v[2:17]
	s_add_u32 m0, vcc_lo, 0xb000
	ds_read_b128 v[90:93], v241 offset:4096
	global_load_lds_dwordx4 v209, s[36:37]
	v_mfma_f32_32x32x16_bf16 v[34:49], v[190:193], v[198:201], v[34:49]
	ds_read_b128 v[94:97], v237 offset:4096
	s_waitcnt lgkmcnt(6)
	v_mfma_f32_32x32x16_bf16 v[50:65], v[66:69], v[70:73], v[50:65]
	s_add_u32 m0, vcc_lo, 0xc000
	ds_read_b128 v[168:171], v238
	global_load_lds_dwordx4 v210, s[38:39]
	s_waitcnt lgkmcnt(5)
	v_mfma_f32_32x32x16_bf16 v[18:33], v[78:81], v[70:73], v[18:33]
	ds_read_b128 v[172:175], v242
	v_mfma_f32_32x32x16_bf16 v[2:17], v[78:81], v[74:77], v[2:17]
	s_add_u32 m0, vcc_lo, 0xd000
	ds_read_b128 v[176:179], v242 offset:4096
	global_load_lds_dwordx4 v211, s[38:39]
	v_mfma_f32_32x32x16_bf16 v[34:49], v[66:69], v[74:77], v[34:49]
	ds_read_b128 v[180:183], v238 offset:4096
	s_waitcnt lgkmcnt(6)
	v_mfma_f32_32x32x16_bf16 v[50:65], v[82:85], v[86:89], v[50:65]
	s_add_u32 m0, vcc_lo, 0xe000
	ds_read_b128 v[190:193], v239
	global_load_lds_dwordx4 v212, s[38:39]
	s_waitcnt lgkmcnt(5)
	v_mfma_f32_32x32x16_bf16 v[18:33], v[94:97], v[86:89], v[18:33]
	ds_read_b128 v[194:197], v243
	v_mfma_f32_32x32x16_bf16 v[2:17], v[94:97], v[90:93], v[2:17]
	s_add_u32 m0, vcc_lo, 0xf000
	ds_read_b128 v[198:201], v243 offset:4096
	global_load_lds_dwordx4 v213, s[38:39]
	v_mfma_f32_32x32x16_bf16 v[34:49], v[82:85], v[90:93], v[34:49]
	ds_read_b128 v[202:205], v239 offset:4096
	s_add_u32 s36, s36, 0x80
	s_addc_u32 s37, s37, 0
	s_add_u32 s38, s38, 0x80
	s_addc_u32 s39, s39, 0
	s_waitcnt vmcnt(0) lgkmcnt(0)
	s_barrier
	v_mfma_f32_32x32x16_bf16 v[50:65], v[168:171], v[172:175], v[50:65]
	s_mov_b32 m0, vcc_lo
	ds_read_b128 v[66:69], v236 offset:32768
	global_load_lds_dwordx4 v206, s[36:37]
	s_setprio 3
	v_mfma_f32_32x32x16_bf16 v[18:33], v[180:183], v[172:175], v[18:33]
	ds_read_b128 v[70:73], v240 offset:32768
	v_mfma_f32_32x32x16_bf16 v[2:17], v[180:183], v[176:179], v[2:17]
	s_add_u32 m0, vcc_lo, 0x1000
	ds_read_b128 v[74:77], v240 offset:36864
	global_load_lds_dwordx4 v207, s[36:37]
	v_mfma_f32_32x32x16_bf16 v[34:49], v[168:171], v[176:179], v[34:49]
	ds_read_b128 v[78:81], v236 offset:36864
	v_mfma_f32_32x32x16_bf16 v[50:65], v[190:193], v[194:197], v[50:65]
	s_add_u32 m0, vcc_lo, 0x2000
	ds_read_b128 v[82:85], v237 offset:32768
	global_load_lds_dwordx4 v208, s[36:37]
	v_mfma_f32_32x32x16_bf16 v[18:33], v[202:205], v[194:197], v[18:33]
	ds_read_b128 v[86:89], v241 offset:32768
	v_mfma_f32_32x32x16_bf16 v[2:17], v[202:205], v[198:201], v[2:17]
	s_add_u32 m0, vcc_lo, 0x3000
	ds_read_b128 v[90:93], v241 offset:36864
	global_load_lds_dwordx4 v209, s[36:37]
	v_mfma_f32_32x32x16_bf16 v[34:49], v[190:193], v[198:201], v[34:49]
	ds_read_b128 v[94:97], v237 offset:36864
	s_waitcnt lgkmcnt(6)
	v_mfma_f32_32x32x16_bf16 v[50:65], v[66:69], v[70:73], v[50:65]
	s_add_u32 m0, vcc_lo, 0x4000
	ds_read_b128 v[168:171], v238 offset:32768
	global_load_lds_dwordx4 v210, s[38:39]
	s_waitcnt lgkmcnt(5)
	v_mfma_f32_32x32x16_bf16 v[18:33], v[78:81], v[70:73], v[18:33]
	ds_read_b128 v[172:175], v242 offset:32768
	v_mfma_f32_32x32x16_bf16 v[2:17], v[78:81], v[74:77], v[2:17]
	s_add_u32 m0, vcc_lo, 0x5000
	ds_read_b128 v[176:179], v242 offset:36864
	global_load_lds_dwordx4 v211, s[38:39]
	v_mfma_f32_32x32x16_bf16 v[34:49], v[66:69], v[74:77], v[34:49]
	ds_read_b128 v[180:183], v238 offset:36864
	s_waitcnt lgkmcnt(6)
	v_mfma_f32_32x32x16_bf16 v[50:65], v[82:85], v[86:89], v[50:65]
	s_add_u32 m0, vcc_lo, 0x6000
	ds_read_b128 v[190:193], v239 offset:32768
	global_load_lds_dwordx4 v212, s[38:39]
	s_waitcnt lgkmcnt(5)
	v_mfma_f32_32x32x16_bf16 v[18:33], v[94:97], v[86:89], v[18:33]
	ds_read_b128 v[194:197], v243 offset:32768
	v_mfma_f32_32x32x16_bf16 v[2:17], v[94:97], v[90:93], v[2:17]
	s_add_u32 m0, vcc_lo, 0x7000
	ds_read_b128 v[198:201], v243 offset:36864
	global_load_lds_dwordx4 v213, s[38:39]
	v_mfma_f32_32x32x16_bf16 v[34:49], v[82:85], v[90:93], v[34:49]
	ds_read_b128 v[202:205], v239 offset:36864
	s_add_u32 s36, s36, 0x80
	s_addc_u32 s37, s37, 0
	s_add_u32 s38, s38, 0x80
	s_addc_u32 s39, s39, 0
	s_waitcnt vmcnt(0) lgkmcnt(0)
	s_barrier
	v_mfma_f32_32x32x16_bf16 v[50:65], v[168:171], v[172:175], v[50:65]
	s_add_u32 m0, vcc_lo, 0x8000
	ds_read_b128 v[66:69], v236
	global_load_lds_dwordx4 v206, s[36:37]
	s_setprio 3
	v_mfma_f32_32x32x16_bf16 v[18:33], v[180:183], v[172:175], v[18:33]
	ds_read_b128 v[70:73], v240
	v_mfma_f32_32x32x16_bf16 v[2:17], v[180:183], v[176:179], v[2:17]
	s_add_u32 m0, vcc_lo, 0x9000
	ds_read_b128 v[74:77], v240 offset:4096
	global_load_lds_dwordx4 v207, s[36:37]
	v_mfma_f32_32x32x16_bf16 v[34:49], v[168:171], v[176:179], v[34:49]
	ds_read_b128 v[78:81], v236 offset:4096
	v_mfma_f32_32x32x16_bf16 v[50:65], v[190:193], v[194:197], v[50:65]
	s_add_u32 m0, vcc_lo, 0xa000
	ds_read_b128 v[82:85], v237
	global_load_lds_dwordx4 v208, s[36:37]
	v_mfma_f32_32x32x16_bf16 v[18:33], v[202:205], v[194:197], v[18:33]
	ds_read_b128 v[86:89], v241
	v_mfma_f32_32x32x16_bf16 v[2:17], v[202:205], v[198:201], v[2:17]
	s_add_u32 m0, vcc_lo, 0xb000
	ds_read_b128 v[90:93], v241 offset:4096
	global_load_lds_dwordx4 v209, s[36:37]
	v_mfma_f32_32x32x16_bf16 v[34:49], v[190:193], v[198:201], v[34:49]
	ds_read_b128 v[94:97], v237 offset:4096
	s_waitcnt lgkmcnt(6)
	v_mfma_f32_32x32x16_bf16 v[50:65], v[66:69], v[70:73], v[50:65]
	s_add_u32 m0, vcc_lo, 0xc000
	ds_read_b128 v[168:171], v238
	global_load_lds_dwordx4 v210, s[38:39]
	s_waitcnt lgkmcnt(5)
	v_mfma_f32_32x32x16_bf16 v[18:33], v[78:81], v[70:73], v[18:33]
	ds_read_b128 v[172:175], v242
	v_mfma_f32_32x32x16_bf16 v[2:17], v[78:81], v[74:77], v[2:17]
	s_add_u32 m0, vcc_lo, 0xd000
	ds_read_b128 v[176:179], v242 offset:4096
	global_load_lds_dwordx4 v211, s[38:39]
	v_mfma_f32_32x32x16_bf16 v[34:49], v[66:69], v[74:77], v[34:49]
	ds_read_b128 v[180:183], v238 offset:4096
	s_waitcnt lgkmcnt(6)
	v_mfma_f32_32x32x16_bf16 v[50:65], v[82:85], v[86:89], v[50:65]
	s_add_u32 m0, vcc_lo, 0xe000
	ds_read_b128 v[190:193], v239
	global_load_lds_dwordx4 v212, s[38:39]
	s_waitcnt lgkmcnt(5)
	v_mfma_f32_32x32x16_bf16 v[18:33], v[94:97], v[86:89], v[18:33]
	ds_read_b128 v[194:197], v243
	v_mfma_f32_32x32x16_bf16 v[2:17], v[94:97], v[90:93], v[2:17]
	s_add_u32 m0, vcc_lo, 0xf000
	ds_read_b128 v[198:201], v243 offset:4096
	global_load_lds_dwordx4 v213, s[38:39]
	v_mfma_f32_32x32x16_bf16 v[34:49], v[82:85], v[90:93], v[34:49]
	ds_read_b128 v[202:205], v239 offset:4096
	s_add_u32 s36, s36, 0x80
	s_addc_u32 s37, s37, 0
	s_add_u32 s38, s38, 0x80
	s_addc_u32 s39, s39, 0
	s_waitcnt vmcnt(0) lgkmcnt(0)
	s_barrier
	v_mfma_f32_32x32x16_bf16 v[50:65], v[168:171], v[172:175], v[50:65]
	s_mov_b32 m0, vcc_lo
	ds_read_b128 v[66:69], v236 offset:32768
	global_load_lds_dwordx4 v206, s[36:37]
	s_setprio 3
	v_mfma_f32_32x32x16_bf16 v[18:33], v[180:183], v[172:175], v[18:33]
	ds_read_b128 v[70:73], v240 offset:32768
	v_mfma_f32_32x32x16_bf16 v[2:17], v[180:183], v[176:179], v[2:17]
	s_add_u32 m0, vcc_lo, 0x1000
	ds_read_b128 v[74:77], v240 offset:36864
	global_load_lds_dwordx4 v207, s[36:37]
	v_mfma_f32_32x32x16_bf16 v[34:49], v[168:171], v[176:179], v[34:49]
	ds_read_b128 v[78:81], v236 offset:36864
	v_mfma_f32_32x32x16_bf16 v[50:65], v[190:193], v[194:197], v[50:65]
	s_add_u32 m0, vcc_lo, 0x2000
	ds_read_b128 v[82:85], v237 offset:32768
	global_load_lds_dwordx4 v208, s[36:37]
	v_mfma_f32_32x32x16_bf16 v[18:33], v[202:205], v[194:197], v[18:33]
	ds_read_b128 v[86:89], v241 offset:32768
	v_mfma_f32_32x32x16_bf16 v[2:17], v[202:205], v[198:201], v[2:17]
	s_add_u32 m0, vcc_lo, 0x3000
	ds_read_b128 v[90:93], v241 offset:36864
	global_load_lds_dwordx4 v209, s[36:37]
	v_mfma_f32_32x32x16_bf16 v[34:49], v[190:193], v[198:201], v[34:49]
	ds_read_b128 v[94:97], v237 offset:36864
	s_waitcnt lgkmcnt(6)
	v_mfma_f32_32x32x16_bf16 v[50:65], v[66:69], v[70:73], v[50:65]
	s_add_u32 m0, vcc_lo, 0x4000
	ds_read_b128 v[168:171], v238 offset:32768
	global_load_lds_dwordx4 v210, s[38:39]
	s_waitcnt lgkmcnt(5)
	v_mfma_f32_32x32x16_bf16 v[18:33], v[78:81], v[70:73], v[18:33]
	ds_read_b128 v[172:175], v242 offset:32768
	v_mfma_f32_32x32x16_bf16 v[2:17], v[78:81], v[74:77], v[2:17]
	s_add_u32 m0, vcc_lo, 0x5000
	ds_read_b128 v[176:179], v242 offset:36864
	global_load_lds_dwordx4 v211, s[38:39]
	v_mfma_f32_32x32x16_bf16 v[34:49], v[66:69], v[74:77], v[34:49]
	ds_read_b128 v[180:183], v238 offset:36864
	s_waitcnt lgkmcnt(6)
	v_mfma_f32_32x32x16_bf16 v[50:65], v[82:85], v[86:89], v[50:65]
	s_add_u32 m0, vcc_lo, 0x6000
	ds_read_b128 v[190:193], v239 offset:32768
	global_load_lds_dwordx4 v212, s[38:39]
	s_waitcnt lgkmcnt(5)
	v_mfma_f32_32x32x16_bf16 v[18:33], v[94:97], v[86:89], v[18:33]
	ds_read_b128 v[194:197], v243 offset:32768
	v_mfma_f32_32x32x16_bf16 v[2:17], v[94:97], v[90:93], v[2:17]
	s_add_u32 m0, vcc_lo, 0x7000
	ds_read_b128 v[198:201], v243 offset:36864
	global_load_lds_dwordx4 v213, s[38:39]
	v_mfma_f32_32x32x16_bf16 v[34:49], v[82:85], v[90:93], v[34:49]
	ds_read_b128 v[202:205], v239 offset:36864
	s_add_u32 s36, s36, 0x80
	s_addc_u32 s37, s37, 0
	s_add_u32 s38, s38, 0x80
	s_addc_u32 s39, s39, 0
	s_waitcnt vmcnt(0) lgkmcnt(0)
	s_barrier
	v_mfma_f32_32x32x16_bf16 v[50:65], v[168:171], v[172:175], v[50:65]
	s_add_u32 m0, vcc_lo, 0x8000
	ds_read_b128 v[66:69], v236
	global_load_lds_dwordx4 v206, s[36:37]
	s_setprio 3
	v_mfma_f32_32x32x16_bf16 v[18:33], v[180:183], v[172:175], v[18:33]
	ds_read_b128 v[70:73], v240
	v_mfma_f32_32x32x16_bf16 v[2:17], v[180:183], v[176:179], v[2:17]
	s_add_u32 m0, vcc_lo, 0x9000
	ds_read_b128 v[74:77], v240 offset:4096
	global_load_lds_dwordx4 v207, s[36:37]
	v_mfma_f32_32x32x16_bf16 v[34:49], v[168:171], v[176:179], v[34:49]
	ds_read_b128 v[78:81], v236 offset:4096
	v_mfma_f32_32x32x16_bf16 v[50:65], v[190:193], v[194:197], v[50:65]
	s_add_u32 m0, vcc_lo, 0xa000
	ds_read_b128 v[82:85], v237
	global_load_lds_dwordx4 v208, s[36:37]
	v_mfma_f32_32x32x16_bf16 v[18:33], v[202:205], v[194:197], v[18:33]
	ds_read_b128 v[86:89], v241
	v_mfma_f32_32x32x16_bf16 v[2:17], v[202:205], v[198:201], v[2:17]
	s_add_u32 m0, vcc_lo, 0xb000
	ds_read_b128 v[90:93], v241 offset:4096
	global_load_lds_dwordx4 v209, s[36:37]
	v_mfma_f32_32x32x16_bf16 v[34:49], v[190:193], v[198:201], v[34:49]
	ds_read_b128 v[94:97], v237 offset:4096
	s_waitcnt lgkmcnt(6)
	v_mfma_f32_32x32x16_bf16 v[50:65], v[66:69], v[70:73], v[50:65]
	s_add_u32 m0, vcc_lo, 0xc000
	ds_read_b128 v[168:171], v238
	global_load_lds_dwordx4 v210, s[38:39]
	s_waitcnt lgkmcnt(5)
	v_mfma_f32_32x32x16_bf16 v[18:33], v[78:81], v[70:73], v[18:33]
	ds_read_b128 v[172:175], v242
	v_mfma_f32_32x32x16_bf16 v[2:17], v[78:81], v[74:77], v[2:17]
	s_add_u32 m0, vcc_lo, 0xd000
	ds_read_b128 v[176:179], v242 offset:4096
	global_load_lds_dwordx4 v211, s[38:39]
	v_mfma_f32_32x32x16_bf16 v[34:49], v[66:69], v[74:77], v[34:49]
	ds_read_b128 v[180:183], v238 offset:4096
	s_waitcnt lgkmcnt(6)
	v_mfma_f32_32x32x16_bf16 v[50:65], v[82:85], v[86:89], v[50:65]
	s_add_u32 m0, vcc_lo, 0xe000
	ds_read_b128 v[190:193], v239
	global_load_lds_dwordx4 v212, s[38:39]
	s_waitcnt lgkmcnt(5)
	v_mfma_f32_32x32x16_bf16 v[18:33], v[94:97], v[86:89], v[18:33]
	ds_read_b128 v[194:197], v243
	v_mfma_f32_32x32x16_bf16 v[2:17], v[94:97], v[90:93], v[2:17]
	s_add_u32 m0, vcc_lo, 0xf000
	ds_read_b128 v[198:201], v243 offset:4096
	global_load_lds_dwordx4 v213, s[38:39]
	v_mfma_f32_32x32x16_bf16 v[34:49], v[82:85], v[90:93], v[34:49]
	ds_read_b128 v[202:205], v239 offset:4096
	s_add_u32 s36, s36, 0x80
	s_addc_u32 s37, s37, 0
	s_add_u32 s38, s38, 0x80
	s_addc_u32 s39, s39, 0
	s_waitcnt vmcnt(0) lgkmcnt(0)
	s_barrier
	v_mfma_f32_32x32x16_bf16 v[50:65], v[168:171], v[172:175], v[50:65]
	s_mov_b32 m0, vcc_lo
	ds_read_b128 v[66:69], v236 offset:32768
	global_load_lds_dwordx4 v206, s[36:37]
	s_setprio 3
	v_mfma_f32_32x32x16_bf16 v[18:33], v[180:183], v[172:175], v[18:33]
	ds_read_b128 v[70:73], v240 offset:32768
	v_mfma_f32_32x32x16_bf16 v[2:17], v[180:183], v[176:179], v[2:17]
	s_add_u32 m0, vcc_lo, 0x1000
	ds_read_b128 v[74:77], v240 offset:36864
	global_load_lds_dwordx4 v207, s[36:37]
	v_mfma_f32_32x32x16_bf16 v[34:49], v[168:171], v[176:179], v[34:49]
	ds_read_b128 v[78:81], v236 offset:36864
	v_mfma_f32_32x32x16_bf16 v[50:65], v[190:193], v[194:197], v[50:65]
	s_add_u32 m0, vcc_lo, 0x2000
	ds_read_b128 v[82:85], v237 offset:32768
	global_load_lds_dwordx4 v208, s[36:37]
	v_mfma_f32_32x32x16_bf16 v[18:33], v[202:205], v[194:197], v[18:33]
	ds_read_b128 v[86:89], v241 offset:32768
	v_mfma_f32_32x32x16_bf16 v[2:17], v[202:205], v[198:201], v[2:17]
	s_add_u32 m0, vcc_lo, 0x3000
	ds_read_b128 v[90:93], v241 offset:36864
	global_load_lds_dwordx4 v209, s[36:37]
	v_mfma_f32_32x32x16_bf16 v[34:49], v[190:193], v[198:201], v[34:49]
	ds_read_b128 v[94:97], v237 offset:36864
	s_waitcnt lgkmcnt(6)
	v_mfma_f32_32x32x16_bf16 v[50:65], v[66:69], v[70:73], v[50:65]
	s_add_u32 m0, vcc_lo, 0x4000
	ds_read_b128 v[168:171], v238 offset:32768
	global_load_lds_dwordx4 v210, s[38:39]
	s_waitcnt lgkmcnt(5)
	v_mfma_f32_32x32x16_bf16 v[18:33], v[78:81], v[70:73], v[18:33]
	ds_read_b128 v[172:175], v242 offset:32768
	v_mfma_f32_32x32x16_bf16 v[2:17], v[78:81], v[74:77], v[2:17]
	s_add_u32 m0, vcc_lo, 0x5000
	ds_read_b128 v[176:179], v242 offset:36864
	global_load_lds_dwordx4 v211, s[38:39]
	v_mfma_f32_32x32x16_bf16 v[34:49], v[66:69], v[74:77], v[34:49]
	ds_read_b128 v[180:183], v238 offset:36864
	s_waitcnt lgkmcnt(6)
	v_mfma_f32_32x32x16_bf16 v[50:65], v[82:85], v[86:89], v[50:65]
	s_add_u32 m0, vcc_lo, 0x6000
	ds_read_b128 v[190:193], v239 offset:32768
	global_load_lds_dwordx4 v212, s[38:39]
	s_waitcnt lgkmcnt(5)
	v_mfma_f32_32x32x16_bf16 v[18:33], v[94:97], v[86:89], v[18:33]
	ds_read_b128 v[194:197], v243 offset:32768
	v_mfma_f32_32x32x16_bf16 v[2:17], v[94:97], v[90:93], v[2:17]
	s_add_u32 m0, vcc_lo, 0x7000
	ds_read_b128 v[198:201], v243 offset:36864
	global_load_lds_dwordx4 v213, s[38:39]
	v_mfma_f32_32x32x16_bf16 v[34:49], v[82:85], v[90:93], v[34:49]
	ds_read_b128 v[202:205], v239 offset:36864
	s_add_u32 s38, s38, 0x80
	s_addc_u32 s39, s39, 0
	s_add_u32 s36, s50, 0x9425000
	s_addc_u32 s37, s51, 0
	s_waitcnt vmcnt(0) lgkmcnt(0)
	s_barrier
	v_mfma_f32_32x32x16_bf16 v[50:65], v[168:171], v[172:175], v[50:65]
	s_add_u32 m0, vcc_lo, 0x8000
	ds_read_b128 v[66:69], v236
	global_load_lds_dwordx4 v222, s[40:41]
	s_setprio 3
	v_mfma_f32_32x32x16_bf16 v[18:33], v[180:183], v[172:175], v[18:33]
	ds_read_b128 v[70:73], v240
	v_mfma_f32_32x32x16_bf16 v[2:17], v[180:183], v[176:179], v[2:17]
	s_add_u32 m0, vcc_lo, 0x9000
	ds_read_b128 v[74:77], v240 offset:4096
	global_load_lds_dwordx4 v223, s[40:41]
	v_mfma_f32_32x32x16_bf16 v[34:49], v[168:171], v[176:179], v[34:49]
	ds_read_b128 v[78:81], v236 offset:4096
	v_mfma_f32_32x32x16_bf16 v[50:65], v[190:193], v[194:197], v[50:65]
	s_add_u32 m0, vcc_lo, 0xa000
	ds_read_b128 v[82:85], v237
	global_load_lds_dwordx4 v224, s[40:41]
	v_mfma_f32_32x32x16_bf16 v[18:33], v[202:205], v[194:197], v[18:33]
	ds_read_b128 v[86:89], v241
	v_mfma_f32_32x32x16_bf16 v[2:17], v[202:205], v[198:201], v[2:17]
	s_add_u32 m0, vcc_lo, 0xb000
	ds_read_b128 v[90:93], v241 offset:4096
	global_load_lds_dwordx4 v225, s[40:41]
	v_mfma_f32_32x32x16_bf16 v[34:49], v[190:193], v[198:201], v[34:49]
	ds_read_b128 v[94:97], v237 offset:4096
	s_waitcnt lgkmcnt(6)
	v_mfma_f32_32x32x16_bf16 v[50:65], v[66:69], v[70:73], v[50:65]
	s_add_u32 m0, vcc_lo, 0xc000
	ds_read_b128 v[168:171], v238
	global_load_lds_dwordx4 v222, s[42:43]
	s_waitcnt lgkmcnt(5)
	v_mfma_f32_32x32x16_bf16 v[18:33], v[78:81], v[70:73], v[18:33]
	ds_read_b128 v[172:175], v242
	v_mfma_f32_32x32x16_bf16 v[2:17], v[78:81], v[74:77], v[2:17]
	s_add_u32 m0, vcc_lo, 0xd000
	ds_read_b128 v[176:179], v242 offset:4096
	global_load_lds_dwordx4 v223, s[42:43]
	v_mfma_f32_32x32x16_bf16 v[34:49], v[66:69], v[74:77], v[34:49]
	ds_read_b128 v[180:183], v238 offset:4096
	s_waitcnt lgkmcnt(6)
	v_mfma_f32_32x32x16_bf16 v[50:65], v[82:85], v[86:89], v[50:65]
	s_add_u32 m0, vcc_lo, 0xe000
	ds_read_b128 v[190:193], v239
	global_load_lds_dwordx4 v224, s[42:43]
	s_waitcnt lgkmcnt(5)
	v_mfma_f32_32x32x16_bf16 v[18:33], v[94:97], v[86:89], v[18:33]
	ds_read_b128 v[194:197], v243
	v_mfma_f32_32x32x16_bf16 v[2:17], v[94:97], v[90:93], v[2:17]
	s_add_u32 m0, vcc_lo, 0xf000
	ds_read_b128 v[198:201], v243 offset:4096
	global_load_lds_dwordx4 v225, s[42:43]
	v_mfma_f32_32x32x16_bf16 v[34:49], v[82:85], v[90:93], v[34:49]
	ds_read_b128 v[202:205], v239 offset:4096
	s_add_u32 s40, s40, 0x800
	s_addc_u32 s41, s41, 0
	s_add_u32 s42, s42, 0x800
	s_addc_u32 s43, s43, 0
	s_waitcnt vmcnt(0) lgkmcnt(0)
	s_barrier
	s_mov_b32 m0, vcc_lo
	v_mfma_f32_32x32x16_bf16 v[50:65], v[168:171], v[172:175], v[50:65]
	global_load_lds_dwordx4 v206, s[36:37]
	s_add_u32 m0, vcc_lo, 0x1000
	v_mfma_f32_32x32x16_bf16 v[18:33], v[180:183], v[172:175], v[18:33]
	global_load_lds_dwordx4 v207, s[36:37]
	s_add_u32 m0, vcc_lo, 0x2000
	v_mfma_f32_32x32x16_bf16 v[2:17], v[180:183], v[176:179], v[2:17]
	global_load_lds_dwordx4 v208, s[36:37]
	s_add_u32 m0, vcc_lo, 0x3000
	v_mfma_f32_32x32x16_bf16 v[34:49], v[168:171], v[176:179], v[34:49]
	global_load_lds_dwordx4 v209, s[36:37]
	s_add_u32 m0, vcc_lo, 0x4000
	v_mfma_f32_32x32x16_bf16 v[50:65], v[190:193], v[194:197], v[50:65]
	global_load_lds_dwordx4 v210, s[38:39]
	s_add_u32 m0, vcc_lo, 0x5000
	v_mfma_f32_32x32x16_bf16 v[18:33], v[202:205], v[194:197], v[18:33]
	global_load_lds_dwordx4 v211, s[38:39]
	s_add_u32 m0, vcc_lo, 0x6000
	v_mfma_f32_32x32x16_bf16 v[2:17], v[202:205], v[198:201], v[2:17]
	global_load_lds_dwordx4 v212, s[38:39]
	s_add_u32 m0, vcc_lo, 0x7000
	v_mfma_f32_32x32x16_bf16 v[34:49], v[190:193], v[198:201], v[34:49]
	global_load_lds_dwordx4 v213, s[38:39]
	s_add_u32 s36, s36, 0x80
	s_addc_u32 s37, s37, 0
	s_add_u32 s38, s38, 0x80
	s_addc_u32 s39, s39, 0
	s_setprio 0
	ds_read_u16 v66, v244 offset:32768
	ds_read_u16 v67, v244 offset:32896
	ds_read_u16 v68, v245 offset:33024
	ds_read_u16 v69, v245 offset:33152
	ds_read_u16 v70, v244 offset:33856
	ds_read_u16 v71, v244 offset:33984
	ds_read_u16 v72, v245 offset:34112
	ds_read_u16 v73, v245 offset:34240
	s_nop 7
	s_nop 7
	ds_read_u16 v74, v244 offset:34816
	ds_read_u16 v75, v244 offset:34944
	ds_read_u16 v76, v245 offset:35072
	ds_read_u16 v77, v245 offset:35200
	ds_read_u16 v78, v244 offset:35904
	ds_read_u16 v79, v244 offset:36032
	ds_read_u16 v80, v245 offset:36160
	ds_read_u16 v81, v245 offset:36288
	s_waitcnt lgkmcnt(8)
	v_lshlrev_b32_e32 v66, 16, v66
	v_lshlrev_b32_e32 v67, 16, v67
	v_lshlrev_b32_e32 v68, 16, v68
	v_lshlrev_b32_e32 v69, 16, v69
	v_mul_f32_e32 v66, 0xbfb8aa3b, v66
	v_mul_f32_e32 v67, 0xbfb8aa3b, v67
	v_mul_f32_e32 v68, 0xbfb8aa3b, v68
	v_mul_f32_e32 v69, 0xbfb8aa3b, v69
	v_exp_f32_e32 v66, v66
	v_exp_f32_e32 v67, v67
	v_exp_f32_e32 v68, v68
	v_exp_f32_e32 v69, v69
	v_add_f32_e32 v66, 1.0, v66
	v_add_f32_e32 v67, 1.0, v67
	v_add_f32_e32 v68, 1.0, v68
	v_add_f32_e32 v69, 1.0, v69
	v_rcp_f32_e32 v66, v66
	v_rcp_f32_e32 v67, v67
	v_rcp_f32_e32 v68, v68
	v_rcp_f32_e32 v69, v69
	s_nop 0
	v_pk_fma_f32 v[166:167], v[50:51], v[66:67], v[166:167]
	v_pk_fma_f32 v[164:165], v[52:53], v[68:69], v[164:165]
	v_lshlrev_b32_e32 v70, 16, v70
	v_lshlrev_b32_e32 v71, 16, v71
	v_lshlrev_b32_e32 v72, 16, v72
	v_lshlrev_b32_e32 v73, 16, v73
	v_mul_f32_e32 v70, 0xbfb8aa3b, v70
	v_mul_f32_e32 v71, 0xbfb8aa3b, v71
	v_mul_f32_e32 v72, 0xbfb8aa3b, v72
	v_mul_f32_e32 v73, 0xbfb8aa3b, v73
	v_exp_f32_e32 v70, v70
	v_exp_f32_e32 v71, v71
	v_exp_f32_e32 v72, v72
	v_exp_f32_e32 v73, v73
	v_add_f32_e32 v70, 1.0, v70
	v_add_f32_e32 v71, 1.0, v71
	v_add_f32_e32 v72, 1.0, v72
	v_add_f32_e32 v73, 1.0, v73
	v_rcp_f32_e32 v70, v70
	v_rcp_f32_e32 v71, v71
	v_rcp_f32_e32 v72, v72
	v_rcp_f32_e32 v73, v73
	s_nop 0
	v_pk_fma_f32 v[162:163], v[54:55], v[70:71], v[162:163]
	v_pk_fma_f32 v[160:161], v[56:57], v[72:73], v[160:161]
	ds_read_u16 v82, v244 offset:36864
	ds_read_u16 v83, v244 offset:36992
	ds_read_u16 v84, v245 offset:37120
	ds_read_u16 v85, v245 offset:37248
	ds_read_u16 v86, v244 offset:37952
	ds_read_u16 v87, v244 offset:38080
	ds_read_u16 v88, v245 offset:38208
	ds_read_u16 v89, v245 offset:38336
	s_waitcnt lgkmcnt(8)
	v_lshlrev_b32_e32 v74, 16, v74
	v_lshlrev_b32_e32 v75, 16, v75
	v_lshlrev_b32_e32 v76, 16, v76
	v_lshlrev_b32_e32 v77, 16, v77
	v_mul_f32_e32 v74, 0xbfb8aa3b, v74
	v_mul_f32_e32 v75, 0xbfb8aa3b, v75
	v_mul_f32_e32 v76, 0xbfb8aa3b, v76
	v_mul_f32_e32 v77, 0xbfb8aa3b, v77
	v_exp_f32_e32 v74, v74
	v_exp_f32_e32 v75, v75
	v_exp_f32_e32 v76, v76
	v_exp_f32_e32 v77, v77
	v_add_f32_e32 v74, 1.0, v74
	v_add_f32_e32 v75, 1.0, v75
	v_add_f32_e32 v76, 1.0, v76
	v_add_f32_e32 v77, 1.0, v77
	v_rcp_f32_e32 v74, v74
	v_rcp_f32_e32 v75, v75
	v_rcp_f32_e32 v76, v76
	v_rcp_f32_e32 v77, v77
	s_nop 0
	v_pk_fma_f32 v[158:159], v[58:59], v[74:75], v[158:159]
	v_pk_fma_f32 v[156:157], v[60:61], v[76:77], v[156:157]
	v_lshlrev_b32_e32 v78, 16, v78
	v_lshlrev_b32_e32 v79, 16, v79
	v_lshlrev_b32_e32 v80, 16, v80
	v_lshlrev_b32_e32 v81, 16, v81
	v_mul_f32_e32 v78, 0xbfb8aa3b, v78
	v_mul_f32_e32 v79, 0xbfb8aa3b, v79
	v_mul_f32_e32 v80, 0xbfb8aa3b, v80
	v_mul_f32_e32 v81, 0xbfb8aa3b, v81
	v_exp_f32_e32 v78, v78
	v_exp_f32_e32 v79, v79
	v_exp_f32_e32 v80, v80
	v_exp_f32_e32 v81, v81
	v_add_f32_e32 v78, 1.0, v78
	v_add_f32_e32 v79, 1.0, v79
	v_add_f32_e32 v80, 1.0, v80
	v_add_f32_e32 v81, 1.0, v81
	v_rcp_f32_e32 v78, v78
	v_rcp_f32_e32 v79, v79
	v_rcp_f32_e32 v80, v80
	v_rcp_f32_e32 v81, v81
	s_nop 0
	v_pk_fma_f32 v[154:155], v[62:63], v[78:79], v[154:155]
	v_pk_fma_f32 v[152:153], v[64:65], v[80:81], v[152:153]
	ds_read_u16 v90, v244 offset:38912
	ds_read_u16 v91, v244 offset:39040
	ds_read_u16 v92, v245 offset:39168
	ds_read_u16 v93, v245 offset:39296
	ds_read_u16 v94, v244 offset:40000
	ds_read_u16 v95, v244 offset:40128
	ds_read_u16 v96, v245 offset:40256
	ds_read_u16 v97, v245 offset:40384
	s_waitcnt lgkmcnt(8)
	v_lshlrev_b32_e32 v82, 16, v82
	v_lshlrev_b32_e32 v83, 16, v83
	v_lshlrev_b32_e32 v84, 16, v84
	v_lshlrev_b32_e32 v85, 16, v85
	v_mul_f32_e32 v82, 0xbfb8aa3b, v82
	v_mul_f32_e32 v83, 0xbfb8aa3b, v83
	v_mul_f32_e32 v84, 0xbfb8aa3b, v84
	v_mul_f32_e32 v85, 0xbfb8aa3b, v85
	v_exp_f32_e32 v82, v82
	v_exp_f32_e32 v83, v83
	v_exp_f32_e32 v84, v84
	v_exp_f32_e32 v85, v85
	v_add_f32_e32 v82, 1.0, v82
	v_add_f32_e32 v83, 1.0, v83
	v_add_f32_e32 v84, 1.0, v84
	v_add_f32_e32 v85, 1.0, v85
	v_rcp_f32_e32 v82, v82
	v_rcp_f32_e32 v83, v83
	v_rcp_f32_e32 v84, v84
	v_rcp_f32_e32 v85, v85
	s_nop 0
	v_pk_fma_f32 v[130:131], v[18:19], v[82:83], v[130:131]
	v_pk_fma_f32 v[128:129], v[20:21], v[84:85], v[128:129]
	v_lshlrev_b32_e32 v86, 16, v86
	v_lshlrev_b32_e32 v87, 16, v87
	v_lshlrev_b32_e32 v88, 16, v88
	v_lshlrev_b32_e32 v89, 16, v89
	v_mul_f32_e32 v86, 0xbfb8aa3b, v86
	v_mul_f32_e32 v87, 0xbfb8aa3b, v87
	v_mul_f32_e32 v88, 0xbfb8aa3b, v88
	v_mul_f32_e32 v89, 0xbfb8aa3b, v89
	v_exp_f32_e32 v86, v86
	v_exp_f32_e32 v87, v87
	v_exp_f32_e32 v88, v88
	v_exp_f32_e32 v89, v89
	v_add_f32_e32 v86, 1.0, v86
	v_add_f32_e32 v87, 1.0, v87
	v_add_f32_e32 v88, 1.0, v88
	v_add_f32_e32 v89, 1.0, v89
	v_rcp_f32_e32 v86, v86
	v_rcp_f32_e32 v87, v87
	v_rcp_f32_e32 v88, v88
	v_rcp_f32_e32 v89, v89
	s_nop 0
	v_pk_fma_f32 v[126:127], v[22:23], v[86:87], v[126:127]
	v_pk_fma_f32 v[124:125], v[24:25], v[88:89], v[124:125]
	ds_read_u16 v168, v244 offset:36928
	ds_read_u16 v169, v244 offset:37056
	ds_read_u16 v170, v245 offset:37184
	ds_read_u16 v171, v245 offset:37312
	ds_read_u16 v172, v244 offset:37888
	ds_read_u16 v173, v244 offset:38016
	ds_read_u16 v174, v245 offset:38144
	ds_read_u16 v175, v245 offset:38272
	s_waitcnt lgkmcnt(8)
	v_lshlrev_b32_e32 v90, 16, v90
	v_lshlrev_b32_e32 v91, 16, v91
	v_lshlrev_b32_e32 v92, 16, v92
	v_lshlrev_b32_e32 v93, 16, v93
	v_mul_f32_e32 v90, 0xbfb8aa3b, v90
	v_mul_f32_e32 v91, 0xbfb8aa3b, v91
	v_mul_f32_e32 v92, 0xbfb8aa3b, v92
	v_mul_f32_e32 v93, 0xbfb8aa3b, v93
	v_exp_f32_e32 v90, v90
	v_exp_f32_e32 v91, v91
	v_exp_f32_e32 v92, v92
	v_exp_f32_e32 v93, v93
	v_add_f32_e32 v90, 1.0, v90
	v_add_f32_e32 v91, 1.0, v91
	v_add_f32_e32 v92, 1.0, v92
	v_add_f32_e32 v93, 1.0, v93
	v_rcp_f32_e32 v90, v90
	v_rcp_f32_e32 v91, v91
	v_rcp_f32_e32 v92, v92
	v_rcp_f32_e32 v93, v93
	s_nop 0
	v_pk_fma_f32 v[122:123], v[26:27], v[90:91], v[122:123]
	v_pk_fma_f32 v[120:121], v[28:29], v[92:93], v[120:121]
	v_lshlrev_b32_e32 v94, 16, v94
	v_lshlrev_b32_e32 v95, 16, v95
	v_lshlrev_b32_e32 v96, 16, v96
	v_lshlrev_b32_e32 v97, 16, v97
	v_mul_f32_e32 v94, 0xbfb8aa3b, v94
	v_mul_f32_e32 v95, 0xbfb8aa3b, v95
	v_mul_f32_e32 v96, 0xbfb8aa3b, v96
	v_mul_f32_e32 v97, 0xbfb8aa3b, v97
	v_exp_f32_e32 v94, v94
	v_exp_f32_e32 v95, v95
	v_exp_f32_e32 v96, v96
	v_exp_f32_e32 v97, v97
	v_add_f32_e32 v94, 1.0, v94
	v_add_f32_e32 v95, 1.0, v95
	v_add_f32_e32 v96, 1.0, v96
	v_add_f32_e32 v97, 1.0, v97
	v_rcp_f32_e32 v94, v94
	v_rcp_f32_e32 v95, v95
	v_rcp_f32_e32 v96, v96
	v_rcp_f32_e32 v97, v97
	s_nop 0
	v_pk_fma_f32 v[118:119], v[30:31], v[94:95], v[118:119]
	v_pk_fma_f32 v[116:117], v[32:33], v[96:97], v[116:117]
	ds_read_u16 v176, v244 offset:38976
	ds_read_u16 v177, v244 offset:39104
	ds_read_u16 v178, v245 offset:39232
	ds_read_u16 v179, v245 offset:39360
	ds_read_u16 v180, v244 offset:39936
	ds_read_u16 v181, v244 offset:40064
	ds_read_u16 v182, v245 offset:40192
	ds_read_u16 v183, v245 offset:40320
	s_waitcnt lgkmcnt(8)
	v_lshlrev_b32_e32 v168, 16, v168
	v_lshlrev_b32_e32 v169, 16, v169
	v_lshlrev_b32_e32 v170, 16, v170
	v_lshlrev_b32_e32 v171, 16, v171
	v_mul_f32_e32 v168, 0xbfb8aa3b, v168
	v_mul_f32_e32 v169, 0xbfb8aa3b, v169
	v_mul_f32_e32 v170, 0xbfb8aa3b, v170
	v_mul_f32_e32 v171, 0xbfb8aa3b, v171
	v_exp_f32_e32 v168, v168
	v_exp_f32_e32 v169, v169
	v_exp_f32_e32 v170, v170
	v_exp_f32_e32 v171, v171
	v_add_f32_e32 v168, 1.0, v168
	v_add_f32_e32 v169, 1.0, v169
	v_add_f32_e32 v170, 1.0, v170
	v_add_f32_e32 v171, 1.0, v171
	v_rcp_f32_e32 v168, v168
	v_rcp_f32_e32 v169, v169
	v_rcp_f32_e32 v170, v170
	v_rcp_f32_e32 v171, v171
	s_nop 0
	v_pk_fma_f32 v[114:115], v[2:3], v[168:169], v[114:115]
	v_pk_fma_f32 v[112:113], v[4:5], v[170:171], v[112:113]
	v_lshlrev_b32_e32 v172, 16, v172
	v_lshlrev_b32_e32 v173, 16, v173
	v_lshlrev_b32_e32 v174, 16, v174
	v_lshlrev_b32_e32 v175, 16, v175
	v_mul_f32_e32 v172, 0xbfb8aa3b, v172
	v_mul_f32_e32 v173, 0xbfb8aa3b, v173
	v_mul_f32_e32 v174, 0xbfb8aa3b, v174
	v_mul_f32_e32 v175, 0xbfb8aa3b, v175
	v_exp_f32_e32 v172, v172
	v_exp_f32_e32 v173, v173
	v_exp_f32_e32 v174, v174
	v_exp_f32_e32 v175, v175
	v_add_f32_e32 v172, 1.0, v172
	v_add_f32_e32 v173, 1.0, v173
	v_add_f32_e32 v174, 1.0, v174
	v_add_f32_e32 v175, 1.0, v175
	v_rcp_f32_e32 v172, v172
	v_rcp_f32_e32 v173, v173
	v_rcp_f32_e32 v174, v174
	v_rcp_f32_e32 v175, v175
	s_nop 0
	v_pk_fma_f32 v[110:111], v[6:7], v[172:173], v[110:111]
	v_pk_fma_f32 v[108:109], v[8:9], v[174:175], v[108:109]
	ds_read_u16 v190, v244 offset:32832
	ds_read_u16 v191, v244 offset:32960
	ds_read_u16 v192, v245 offset:33088
	ds_read_u16 v193, v245 offset:33216
	ds_read_u16 v194, v244 offset:33792
	ds_read_u16 v195, v244 offset:33920
	ds_read_u16 v196, v245 offset:34048
	ds_read_u16 v197, v245 offset:34176
	s_waitcnt lgkmcnt(8)
	v_lshlrev_b32_e32 v176, 16, v176
	v_lshlrev_b32_e32 v177, 16, v177
	v_lshlrev_b32_e32 v178, 16, v178
	v_lshlrev_b32_e32 v179, 16, v179
	v_mul_f32_e32 v176, 0xbfb8aa3b, v176
	v_mul_f32_e32 v177, 0xbfb8aa3b, v177
	v_mul_f32_e32 v178, 0xbfb8aa3b, v178
	v_mul_f32_e32 v179, 0xbfb8aa3b, v179
	v_exp_f32_e32 v176, v176
	v_exp_f32_e32 v177, v177
	v_exp_f32_e32 v178, v178
	v_exp_f32_e32 v179, v179
	v_add_f32_e32 v176, 1.0, v176
	v_add_f32_e32 v177, 1.0, v177
	v_add_f32_e32 v178, 1.0, v178
	v_add_f32_e32 v179, 1.0, v179
	v_rcp_f32_e32 v176, v176
	v_rcp_f32_e32 v177, v177
	v_rcp_f32_e32 v178, v178
	v_rcp_f32_e32 v179, v179
	s_nop 0
	v_pk_fma_f32 v[106:107], v[10:11], v[176:177], v[106:107]
	v_pk_fma_f32 v[104:105], v[12:13], v[178:179], v[104:105]
	v_lshlrev_b32_e32 v180, 16, v180
	v_lshlrev_b32_e32 v181, 16, v181
	v_lshlrev_b32_e32 v182, 16, v182
	v_lshlrev_b32_e32 v183, 16, v183
	v_mul_f32_e32 v180, 0xbfb8aa3b, v180
	v_mul_f32_e32 v181, 0xbfb8aa3b, v181
	v_mul_f32_e32 v182, 0xbfb8aa3b, v182
	v_mul_f32_e32 v183, 0xbfb8aa3b, v183
	v_exp_f32_e32 v180, v180
	v_exp_f32_e32 v181, v181
	v_exp_f32_e32 v182, v182
	v_exp_f32_e32 v183, v183
	v_add_f32_e32 v180, 1.0, v180
	v_add_f32_e32 v181, 1.0, v181
	v_add_f32_e32 v182, 1.0, v182
	v_add_f32_e32 v183, 1.0, v183
	v_rcp_f32_e32 v180, v180
	v_rcp_f32_e32 v181, v181
	v_rcp_f32_e32 v182, v182
	v_rcp_f32_e32 v183, v183
	s_nop 0
	v_pk_fma_f32 v[102:103], v[14:15], v[180:181], v[102:103]
	v_pk_fma_f32 v[100:101], v[16:17], v[182:183], v[100:101]
	ds_read_u16 v198, v244 offset:34880
	ds_read_u16 v199, v244 offset:35008
	ds_read_u16 v200, v245 offset:35136
	ds_read_u16 v201, v245 offset:35264
	ds_read_u16 v202, v244 offset:35840
	ds_read_u16 v203, v244 offset:35968
	ds_read_u16 v204, v245 offset:36096
	ds_read_u16 v205, v245 offset:36224
	s_waitcnt lgkmcnt(8)
	v_lshlrev_b32_e32 v190, 16, v190
	v_lshlrev_b32_e32 v191, 16, v191
	v_lshlrev_b32_e32 v192, 16, v192
	v_lshlrev_b32_e32 v193, 16, v193
	v_mul_f32_e32 v190, 0xbfb8aa3b, v190
	v_mul_f32_e32 v191, 0xbfb8aa3b, v191
	v_mul_f32_e32 v192, 0xbfb8aa3b, v192
	v_mul_f32_e32 v193, 0xbfb8aa3b, v193
	v_exp_f32_e32 v190, v190
	v_exp_f32_e32 v191, v191
	v_exp_f32_e32 v192, v192
	v_exp_f32_e32 v193, v193
	v_add_f32_e32 v190, 1.0, v190
	v_add_f32_e32 v191, 1.0, v191
	v_add_f32_e32 v192, 1.0, v192
	v_add_f32_e32 v193, 1.0, v193
	v_rcp_f32_e32 v190, v190
	v_rcp_f32_e32 v191, v191
	v_rcp_f32_e32 v192, v192
	v_rcp_f32_e32 v193, v193
	s_nop 0
	v_pk_fma_f32 v[150:151], v[34:35], v[190:191], v[150:151]
	v_pk_fma_f32 v[148:149], v[36:37], v[192:193], v[148:149]
	v_lshlrev_b32_e32 v194, 16, v194
	v_lshlrev_b32_e32 v195, 16, v195
	v_lshlrev_b32_e32 v196, 16, v196
	v_lshlrev_b32_e32 v197, 16, v197
	v_mul_f32_e32 v194, 0xbfb8aa3b, v194
	v_mul_f32_e32 v195, 0xbfb8aa3b, v195
	v_mul_f32_e32 v196, 0xbfb8aa3b, v196
	v_mul_f32_e32 v197, 0xbfb8aa3b, v197
	v_exp_f32_e32 v194, v194
	v_exp_f32_e32 v195, v195
	v_exp_f32_e32 v196, v196
	v_exp_f32_e32 v197, v197
	v_add_f32_e32 v194, 1.0, v194
	v_add_f32_e32 v195, 1.0, v195
	v_add_f32_e32 v196, 1.0, v196
	v_add_f32_e32 v197, 1.0, v197
	v_rcp_f32_e32 v194, v194
	v_rcp_f32_e32 v195, v195
	v_rcp_f32_e32 v196, v196
	v_rcp_f32_e32 v197, v197
	s_nop 0
	v_pk_fma_f32 v[146:147], v[38:39], v[194:195], v[146:147]
	v_pk_fma_f32 v[142:143], v[40:41], v[196:197], v[142:143]
	s_waitcnt lgkmcnt(0)
	v_lshlrev_b32_e32 v198, 16, v198
	v_lshlrev_b32_e32 v199, 16, v199
	v_lshlrev_b32_e32 v200, 16, v200
	v_lshlrev_b32_e32 v201, 16, v201
	v_mul_f32_e32 v198, 0xbfb8aa3b, v198
	v_mul_f32_e32 v199, 0xbfb8aa3b, v199
	v_mul_f32_e32 v200, 0xbfb8aa3b, v200
	v_mul_f32_e32 v201, 0xbfb8aa3b, v201
	v_exp_f32_e32 v198, v198
	v_exp_f32_e32 v199, v199
	v_exp_f32_e32 v200, v200
	v_exp_f32_e32 v201, v201
	v_add_f32_e32 v198, 1.0, v198
	v_add_f32_e32 v199, 1.0, v199
	v_add_f32_e32 v200, 1.0, v200
	v_add_f32_e32 v201, 1.0, v201
	v_rcp_f32_e32 v198, v198
	v_rcp_f32_e32 v199, v199
	v_rcp_f32_e32 v200, v200
	v_rcp_f32_e32 v201, v201
	s_nop 0
	v_pk_fma_f32 v[140:141], v[42:43], v[198:199], v[140:141]
	v_pk_fma_f32 v[138:139], v[44:45], v[200:201], v[138:139]
	v_lshlrev_b32_e32 v202, 16, v202
	v_lshlrev_b32_e32 v203, 16, v203
	v_lshlrev_b32_e32 v204, 16, v204
	v_lshlrev_b32_e32 v205, 16, v205
	v_mul_f32_e32 v202, 0xbfb8aa3b, v202
	v_mul_f32_e32 v203, 0xbfb8aa3b, v203
	v_mul_f32_e32 v204, 0xbfb8aa3b, v204
	v_mul_f32_e32 v205, 0xbfb8aa3b, v205
	v_exp_f32_e32 v202, v202
	v_exp_f32_e32 v203, v203
	v_exp_f32_e32 v204, v204
	v_exp_f32_e32 v205, v205
	v_add_f32_e32 v202, 1.0, v202
	v_add_f32_e32 v203, 1.0, v203
	v_add_f32_e32 v204, 1.0, v204
	v_add_f32_e32 v205, 1.0, v205
	v_rcp_f32_e32 v202, v202
	v_rcp_f32_e32 v203, v203
	v_rcp_f32_e32 v204, v204
	v_rcp_f32_e32 v205, v205
	s_nop 0
	v_pk_fma_f32 v[136:137], v[46:47], v[202:203], v[136:137]
	v_pk_fma_f32 v[134:135], v[48:49], v[204:205], v[134:135]
	s_waitcnt vmcnt(0) lgkmcnt(0)
	s_barrier
	s_add_u32 m0, vcc_lo, 0x8000
	ds_read_b128 v[66:69], v236
	global_load_lds_dwordx4 v206, s[36:37]
	s_setprio 3
	ds_read_b128 v[70:73], v240
	s_add_u32 m0, vcc_lo, 0x9000
	ds_read_b128 v[74:77], v240 offset:4096
	global_load_lds_dwordx4 v207, s[36:37]
	ds_read_b128 v[78:81], v236 offset:4096
	s_add_u32 m0, vcc_lo, 0xa000
	ds_read_b128 v[82:85], v237
	global_load_lds_dwordx4 v208, s[36:37]
	ds_read_b128 v[86:89], v241
	s_add_u32 m0, vcc_lo, 0xb000
	ds_read_b128 v[90:93], v241 offset:4096
	global_load_lds_dwordx4 v209, s[36:37]
	ds_read_b128 v[94:97], v237 offset:4096
	s_waitcnt lgkmcnt(6)
	v_mfma_f32_32x32x16_bf16 v[50:65], v[66:69], v[70:73], 0
	s_add_u32 m0, vcc_lo, 0xc000
	ds_read_b128 v[168:171], v238
	global_load_lds_dwordx4 v210, s[38:39]
	s_waitcnt lgkmcnt(5)
	v_mfma_f32_32x32x16_bf16 v[18:33], v[78:81], v[70:73], 0
	ds_read_b128 v[172:175], v242
	v_mfma_f32_32x32x16_bf16 v[2:17], v[78:81], v[74:77], 0
	s_add_u32 m0, vcc_lo, 0xd000
	ds_read_b128 v[176:179], v242 offset:4096
	global_load_lds_dwordx4 v211, s[38:39]
	v_mfma_f32_32x32x16_bf16 v[34:49], v[66:69], v[74:77], 0
	ds_read_b128 v[180:183], v238 offset:4096
	s_waitcnt lgkmcnt(6)
	v_mfma_f32_32x32x16_bf16 v[50:65], v[82:85], v[86:89], v[50:65]
	s_add_u32 m0, vcc_lo, 0xe000
	ds_read_b128 v[190:193], v239
	global_load_lds_dwordx4 v212, s[38:39]
	s_waitcnt lgkmcnt(5)
	v_mfma_f32_32x32x16_bf16 v[18:33], v[94:97], v[86:89], v[18:33]
	ds_read_b128 v[194:197], v243
	v_mfma_f32_32x32x16_bf16 v[2:17], v[94:97], v[90:93], v[2:17]
	s_add_u32 m0, vcc_lo, 0xf000
	ds_read_b128 v[198:201], v243 offset:4096
	global_load_lds_dwordx4 v213, s[38:39]
	v_mfma_f32_32x32x16_bf16 v[34:49], v[82:85], v[90:93], v[34:49]
	ds_read_b128 v[202:205], v239 offset:4096
	s_add_u32 s36, s36, 0x80
	s_addc_u32 s37, s37, 0
	s_add_u32 s38, s38, 0x80
	s_addc_u32 s39, s39, 0
	s_waitcnt vmcnt(0) lgkmcnt(0)
	s_barrier
	v_mfma_f32_32x32x16_bf16 v[50:65], v[168:171], v[172:175], v[50:65]
	s_mov_b32 m0, vcc_lo
	ds_read_b128 v[66:69], v236 offset:32768
	global_load_lds_dwordx4 v206, s[36:37]
	s_setprio 3
	v_mfma_f32_32x32x16_bf16 v[18:33], v[180:183], v[172:175], v[18:33]
	ds_read_b128 v[70:73], v240 offset:32768
	v_mfma_f32_32x32x16_bf16 v[2:17], v[180:183], v[176:179], v[2:17]
	s_add_u32 m0, vcc_lo, 0x1000
	ds_read_b128 v[74:77], v240 offset:36864
	global_load_lds_dwordx4 v207, s[36:37]
	v_mfma_f32_32x32x16_bf16 v[34:49], v[168:171], v[176:179], v[34:49]
	ds_read_b128 v[78:81], v236 offset:36864
	v_mfma_f32_32x32x16_bf16 v[50:65], v[190:193], v[194:197], v[50:65]
	s_add_u32 m0, vcc_lo, 0x2000
	ds_read_b128 v[82:85], v237 offset:32768
	global_load_lds_dwordx4 v208, s[36:37]
	v_mfma_f32_32x32x16_bf16 v[18:33], v[202:205], v[194:197], v[18:33]
	ds_read_b128 v[86:89], v241 offset:32768
	v_mfma_f32_32x32x16_bf16 v[2:17], v[202:205], v[198:201], v[2:17]
	s_add_u32 m0, vcc_lo, 0x3000
	ds_read_b128 v[90:93], v241 offset:36864
	global_load_lds_dwordx4 v209, s[36:37]
	v_mfma_f32_32x32x16_bf16 v[34:49], v[190:193], v[198:201], v[34:49]
	ds_read_b128 v[94:97], v237 offset:36864
	s_waitcnt lgkmcnt(6)
	v_mfma_f32_32x32x16_bf16 v[50:65], v[66:69], v[70:73], v[50:65]
	s_add_u32 m0, vcc_lo, 0x4000
	ds_read_b128 v[168:171], v238 offset:32768
	global_load_lds_dwordx4 v210, s[38:39]
	s_waitcnt lgkmcnt(5)
	v_mfma_f32_32x32x16_bf16 v[18:33], v[78:81], v[70:73], v[18:33]
	ds_read_b128 v[172:175], v242 offset:32768
	v_mfma_f32_32x32x16_bf16 v[2:17], v[78:81], v[74:77], v[2:17]
	s_add_u32 m0, vcc_lo, 0x5000
	ds_read_b128 v[176:179], v242 offset:36864
	global_load_lds_dwordx4 v211, s[38:39]
	v_mfma_f32_32x32x16_bf16 v[34:49], v[66:69], v[74:77], v[34:49]
	ds_read_b128 v[180:183], v238 offset:36864
	s_waitcnt lgkmcnt(6)
	v_mfma_f32_32x32x16_bf16 v[50:65], v[82:85], v[86:89], v[50:65]
	s_add_u32 m0, vcc_lo, 0x6000
	ds_read_b128 v[190:193], v239 offset:32768
	global_load_lds_dwordx4 v212, s[38:39]
	s_waitcnt lgkmcnt(5)
	v_mfma_f32_32x32x16_bf16 v[18:33], v[94:97], v[86:89], v[18:33]
	ds_read_b128 v[194:197], v243 offset:32768
	v_mfma_f32_32x32x16_bf16 v[2:17], v[94:97], v[90:93], v[2:17]
	s_add_u32 m0, vcc_lo, 0x7000
	ds_read_b128 v[198:201], v243 offset:36864
	global_load_lds_dwordx4 v213, s[38:39]
	v_mfma_f32_32x32x16_bf16 v[34:49], v[82:85], v[90:93], v[34:49]
	ds_read_b128 v[202:205], v239 offset:36864
	s_add_u32 s36, s36, 0x80
	s_addc_u32 s37, s37, 0
	s_add_u32 s38, s38, 0x80
	s_addc_u32 s39, s39, 0
	s_waitcnt vmcnt(0) lgkmcnt(0)
	s_barrier
	v_mfma_f32_32x32x16_bf16 v[50:65], v[168:171], v[172:175], v[50:65]
	s_add_u32 m0, vcc_lo, 0x8000
	ds_read_b128 v[66:69], v236
	global_load_lds_dwordx4 v206, s[36:37]
	s_setprio 3
	v_mfma_f32_32x32x16_bf16 v[18:33], v[180:183], v[172:175], v[18:33]
	ds_read_b128 v[70:73], v240
	v_mfma_f32_32x32x16_bf16 v[2:17], v[180:183], v[176:179], v[2:17]
	s_add_u32 m0, vcc_lo, 0x9000
	ds_read_b128 v[74:77], v240 offset:4096
	global_load_lds_dwordx4 v207, s[36:37]
	v_mfma_f32_32x32x16_bf16 v[34:49], v[168:171], v[176:179], v[34:49]
	ds_read_b128 v[78:81], v236 offset:4096
	v_mfma_f32_32x32x16_bf16 v[50:65], v[190:193], v[194:197], v[50:65]
	s_add_u32 m0, vcc_lo, 0xa000
	ds_read_b128 v[82:85], v237
	global_load_lds_dwordx4 v208, s[36:37]
	v_mfma_f32_32x32x16_bf16 v[18:33], v[202:205], v[194:197], v[18:33]
	ds_read_b128 v[86:89], v241
	v_mfma_f32_32x32x16_bf16 v[2:17], v[202:205], v[198:201], v[2:17]
	s_add_u32 m0, vcc_lo, 0xb000
	ds_read_b128 v[90:93], v241 offset:4096
	global_load_lds_dwordx4 v209, s[36:37]
	v_mfma_f32_32x32x16_bf16 v[34:49], v[190:193], v[198:201], v[34:49]
	ds_read_b128 v[94:97], v237 offset:4096
	s_waitcnt lgkmcnt(6)
	v_mfma_f32_32x32x16_bf16 v[50:65], v[66:69], v[70:73], v[50:65]
	s_add_u32 m0, vcc_lo, 0xc000
	ds_read_b128 v[168:171], v238
	global_load_lds_dwordx4 v210, s[38:39]
	s_waitcnt lgkmcnt(5)
	v_mfma_f32_32x32x16_bf16 v[18:33], v[78:81], v[70:73], v[18:33]
	ds_read_b128 v[172:175], v242
	v_mfma_f32_32x32x16_bf16 v[2:17], v[78:81], v[74:77], v[2:17]
	s_add_u32 m0, vcc_lo, 0xd000
	ds_read_b128 v[176:179], v242 offset:4096
	global_load_lds_dwordx4 v211, s[38:39]
	v_mfma_f32_32x32x16_bf16 v[34:49], v[66:69], v[74:77], v[34:49]
	ds_read_b128 v[180:183], v238 offset:4096
	s_waitcnt lgkmcnt(6)
	v_mfma_f32_32x32x16_bf16 v[50:65], v[82:85], v[86:89], v[50:65]
	s_add_u32 m0, vcc_lo, 0xe000
	ds_read_b128 v[190:193], v239
	global_load_lds_dwordx4 v212, s[38:39]
	s_waitcnt lgkmcnt(5)
	v_mfma_f32_32x32x16_bf16 v[18:33], v[94:97], v[86:89], v[18:33]
	ds_read_b128 v[194:197], v243
	v_mfma_f32_32x32x16_bf16 v[2:17], v[94:97], v[90:93], v[2:17]
	s_add_u32 m0, vcc_lo, 0xf000
	ds_read_b128 v[198:201], v243 offset:4096
	global_load_lds_dwordx4 v213, s[38:39]
	v_mfma_f32_32x32x16_bf16 v[34:49], v[82:85], v[90:93], v[34:49]
	ds_read_b128 v[202:205], v239 offset:4096
	s_add_u32 s36, s36, 0x80
	s_addc_u32 s37, s37, 0
	s_add_u32 s38, s38, 0x80
	s_addc_u32 s39, s39, 0
	s_waitcnt vmcnt(0) lgkmcnt(0)
	s_barrier
	v_mfma_f32_32x32x16_bf16 v[50:65], v[168:171], v[172:175], v[50:65]
	s_mov_b32 m0, vcc_lo
	ds_read_b128 v[66:69], v236 offset:32768
	global_load_lds_dwordx4 v206, s[36:37]
	s_setprio 3
	v_mfma_f32_32x32x16_bf16 v[18:33], v[180:183], v[172:175], v[18:33]
	ds_read_b128 v[70:73], v240 offset:32768
	v_mfma_f32_32x32x16_bf16 v[2:17], v[180:183], v[176:179], v[2:17]
	s_add_u32 m0, vcc_lo, 0x1000
	ds_read_b128 v[74:77], v240 offset:36864
	global_load_lds_dwordx4 v207, s[36:37]
	v_mfma_f32_32x32x16_bf16 v[34:49], v[168:171], v[176:179], v[34:49]
	ds_read_b128 v[78:81], v236 offset:36864
	v_mfma_f32_32x32x16_bf16 v[50:65], v[190:193], v[194:197], v[50:65]
	s_add_u32 m0, vcc_lo, 0x2000
	ds_read_b128 v[82:85], v237 offset:32768
	global_load_lds_dwordx4 v208, s[36:37]
	v_mfma_f32_32x32x16_bf16 v[18:33], v[202:205], v[194:197], v[18:33]
	ds_read_b128 v[86:89], v241 offset:32768
	v_mfma_f32_32x32x16_bf16 v[2:17], v[202:205], v[198:201], v[2:17]
	s_add_u32 m0, vcc_lo, 0x3000
	ds_read_b128 v[90:93], v241 offset:36864
	global_load_lds_dwordx4 v209, s[36:37]
	v_mfma_f32_32x32x16_bf16 v[34:49], v[190:193], v[198:201], v[34:49]
	ds_read_b128 v[94:97], v237 offset:36864
	s_waitcnt lgkmcnt(6)
	v_mfma_f32_32x32x16_bf16 v[50:65], v[66:69], v[70:73], v[50:65]
	s_add_u32 m0, vcc_lo, 0x4000
	ds_read_b128 v[168:171], v238 offset:32768
	global_load_lds_dwordx4 v210, s[38:39]
	s_waitcnt lgkmcnt(5)
	v_mfma_f32_32x32x16_bf16 v[18:33], v[78:81], v[70:73], v[18:33]
	ds_read_b128 v[172:175], v242 offset:32768
	v_mfma_f32_32x32x16_bf16 v[2:17], v[78:81], v[74:77], v[2:17]
	s_add_u32 m0, vcc_lo, 0x5000
	ds_read_b128 v[176:179], v242 offset:36864
	global_load_lds_dwordx4 v211, s[38:39]
	v_mfma_f32_32x32x16_bf16 v[34:49], v[66:69], v[74:77], v[34:49]
	ds_read_b128 v[180:183], v238 offset:36864
	s_waitcnt lgkmcnt(6)
	v_mfma_f32_32x32x16_bf16 v[50:65], v[82:85], v[86:89], v[50:65]
	s_add_u32 m0, vcc_lo, 0x6000
	ds_read_b128 v[190:193], v239 offset:32768
	global_load_lds_dwordx4 v212, s[38:39]
	s_waitcnt lgkmcnt(5)
	v_mfma_f32_32x32x16_bf16 v[18:33], v[94:97], v[86:89], v[18:33]
	ds_read_b128 v[194:197], v243 offset:32768
	v_mfma_f32_32x32x16_bf16 v[2:17], v[94:97], v[90:93], v[2:17]
	s_add_u32 m0, vcc_lo, 0x7000
	ds_read_b128 v[198:201], v243 offset:36864
	global_load_lds_dwordx4 v213, s[38:39]
	v_mfma_f32_32x32x16_bf16 v[34:49], v[82:85], v[90:93], v[34:49]
	ds_read_b128 v[202:205], v239 offset:36864
	s_add_u32 s36, s36, 0x80
	s_addc_u32 s37, s37, 0
	s_add_u32 s38, s38, 0x80
	s_addc_u32 s39, s39, 0
	s_waitcnt vmcnt(0) lgkmcnt(0)
	s_barrier
	v_mfma_f32_32x32x16_bf16 v[50:65], v[168:171], v[172:175], v[50:65]
	s_add_u32 m0, vcc_lo, 0x8000
	ds_read_b128 v[66:69], v236
	global_load_lds_dwordx4 v206, s[36:37]
	s_setprio 3
	v_mfma_f32_32x32x16_bf16 v[18:33], v[180:183], v[172:175], v[18:33]
	ds_read_b128 v[70:73], v240
	v_mfma_f32_32x32x16_bf16 v[2:17], v[180:183], v[176:179], v[2:17]
	s_add_u32 m0, vcc_lo, 0x9000
	ds_read_b128 v[74:77], v240 offset:4096
	global_load_lds_dwordx4 v207, s[36:37]
	v_mfma_f32_32x32x16_bf16 v[34:49], v[168:171], v[176:179], v[34:49]
	ds_read_b128 v[78:81], v236 offset:4096
	v_mfma_f32_32x32x16_bf16 v[50:65], v[190:193], v[194:197], v[50:65]
	s_add_u32 m0, vcc_lo, 0xa000
	ds_read_b128 v[82:85], v237
	global_load_lds_dwordx4 v208, s[36:37]
	v_mfma_f32_32x32x16_bf16 v[18:33], v[202:205], v[194:197], v[18:33]
	ds_read_b128 v[86:89], v241
	v_mfma_f32_32x32x16_bf16 v[2:17], v[202:205], v[198:201], v[2:17]
	s_add_u32 m0, vcc_lo, 0xb000
	ds_read_b128 v[90:93], v241 offset:4096
	global_load_lds_dwordx4 v209, s[36:37]
	v_mfma_f32_32x32x16_bf16 v[34:49], v[190:193], v[198:201], v[34:49]
	ds_read_b128 v[94:97], v237 offset:4096
	s_waitcnt lgkmcnt(6)
	v_mfma_f32_32x32x16_bf16 v[50:65], v[66:69], v[70:73], v[50:65]
	s_add_u32 m0, vcc_lo, 0xc000
	ds_read_b128 v[168:171], v238
	global_load_lds_dwordx4 v210, s[38:39]
	s_waitcnt lgkmcnt(5)
	v_mfma_f32_32x32x16_bf16 v[18:33], v[78:81], v[70:73], v[18:33]
	ds_read_b128 v[172:175], v242
	v_mfma_f32_32x32x16_bf16 v[2:17], v[78:81], v[74:77], v[2:17]
	s_add_u32 m0, vcc_lo, 0xd000
	ds_read_b128 v[176:179], v242 offset:4096
	global_load_lds_dwordx4 v211, s[38:39]
	v_mfma_f32_32x32x16_bf16 v[34:49], v[66:69], v[74:77], v[34:49]
	ds_read_b128 v[180:183], v238 offset:4096
	s_waitcnt lgkmcnt(6)
	v_mfma_f32_32x32x16_bf16 v[50:65], v[82:85], v[86:89], v[50:65]
	s_add_u32 m0, vcc_lo, 0xe000
	ds_read_b128 v[190:193], v239
	global_load_lds_dwordx4 v212, s[38:39]
	s_waitcnt lgkmcnt(5)
	v_mfma_f32_32x32x16_bf16 v[18:33], v[94:97], v[86:89], v[18:33]
	ds_read_b128 v[194:197], v243
	v_mfma_f32_32x32x16_bf16 v[2:17], v[94:97], v[90:93], v[2:17]
	s_add_u32 m0, vcc_lo, 0xf000
	ds_read_b128 v[198:201], v243 offset:4096
	global_load_lds_dwordx4 v213, s[38:39]
	v_mfma_f32_32x32x16_bf16 v[34:49], v[82:85], v[90:93], v[34:49]
	ds_read_b128 v[202:205], v239 offset:4096
	s_add_u32 s36, s36, 0x80
	s_addc_u32 s37, s37, 0
	s_add_u32 s38, s38, 0x80
	s_addc_u32 s39, s39, 0
	s_waitcnt vmcnt(0) lgkmcnt(0)
	s_barrier
	v_mfma_f32_32x32x16_bf16 v[50:65], v[168:171], v[172:175], v[50:65]
	s_mov_b32 m0, vcc_lo
	ds_read_b128 v[66:69], v236 offset:32768
	global_load_lds_dwordx4 v206, s[36:37]
	s_setprio 3
	v_mfma_f32_32x32x16_bf16 v[18:33], v[180:183], v[172:175], v[18:33]
	ds_read_b128 v[70:73], v240 offset:32768
	v_mfma_f32_32x32x16_bf16 v[2:17], v[180:183], v[176:179], v[2:17]
	s_add_u32 m0, vcc_lo, 0x1000
	ds_read_b128 v[74:77], v240 offset:36864
	global_load_lds_dwordx4 v207, s[36:37]
	v_mfma_f32_32x32x16_bf16 v[34:49], v[168:171], v[176:179], v[34:49]
	ds_read_b128 v[78:81], v236 offset:36864
	v_mfma_f32_32x32x16_bf16 v[50:65], v[190:193], v[194:197], v[50:65]
	s_add_u32 m0, vcc_lo, 0x2000
	ds_read_b128 v[82:85], v237 offset:32768
	global_load_lds_dwordx4 v208, s[36:37]
	v_mfma_f32_32x32x16_bf16 v[18:33], v[202:205], v[194:197], v[18:33]
	ds_read_b128 v[86:89], v241 offset:32768
	v_mfma_f32_32x32x16_bf16 v[2:17], v[202:205], v[198:201], v[2:17]
	s_add_u32 m0, vcc_lo, 0x3000
	ds_read_b128 v[90:93], v241 offset:36864
	global_load_lds_dwordx4 v209, s[36:37]
	v_mfma_f32_32x32x16_bf16 v[34:49], v[190:193], v[198:201], v[34:49]
	ds_read_b128 v[94:97], v237 offset:36864
	s_waitcnt lgkmcnt(6)
	v_mfma_f32_32x32x16_bf16 v[50:65], v[66:69], v[70:73], v[50:65]
	s_add_u32 m0, vcc_lo, 0x4000
	ds_read_b128 v[168:171], v238 offset:32768
	global_load_lds_dwordx4 v210, s[38:39]
	s_waitcnt lgkmcnt(5)
	v_mfma_f32_32x32x16_bf16 v[18:33], v[78:81], v[70:73], v[18:33]
	ds_read_b128 v[172:175], v242 offset:32768
	v_mfma_f32_32x32x16_bf16 v[2:17], v[78:81], v[74:77], v[2:17]
	s_add_u32 m0, vcc_lo, 0x5000
	ds_read_b128 v[176:179], v242 offset:36864
	global_load_lds_dwordx4 v211, s[38:39]
	v_mfma_f32_32x32x16_bf16 v[34:49], v[66:69], v[74:77], v[34:49]
	ds_read_b128 v[180:183], v238 offset:36864
	s_waitcnt lgkmcnt(6)
	v_mfma_f32_32x32x16_bf16 v[50:65], v[82:85], v[86:89], v[50:65]
	s_add_u32 m0, vcc_lo, 0x6000
	ds_read_b128 v[190:193], v239 offset:32768
	global_load_lds_dwordx4 v212, s[38:39]
	s_waitcnt lgkmcnt(5)
	v_mfma_f32_32x32x16_bf16 v[18:33], v[94:97], v[86:89], v[18:33]
	ds_read_b128 v[194:197], v243 offset:32768
	v_mfma_f32_32x32x16_bf16 v[2:17], v[94:97], v[90:93], v[2:17]
	s_add_u32 m0, vcc_lo, 0x7000
	ds_read_b128 v[198:201], v243 offset:36864
	global_load_lds_dwordx4 v213, s[38:39]
	v_mfma_f32_32x32x16_bf16 v[34:49], v[82:85], v[90:93], v[34:49]
	ds_read_b128 v[202:205], v239 offset:36864
	s_add_u32 s36, s36, 0x80
	s_addc_u32 s37, s37, 0
	s_add_u32 s38, s38, 0x80
	s_addc_u32 s39, s39, 0
	s_waitcnt vmcnt(0) lgkmcnt(0)
	s_barrier
	v_mfma_f32_32x32x16_bf16 v[50:65], v[168:171], v[172:175], v[50:65]
	s_add_u32 m0, vcc_lo, 0x8000
	ds_read_b128 v[66:69], v236
	global_load_lds_dwordx4 v206, s[36:37]
	s_setprio 3
	v_mfma_f32_32x32x16_bf16 v[18:33], v[180:183], v[172:175], v[18:33]
	ds_read_b128 v[70:73], v240
	v_mfma_f32_32x32x16_bf16 v[2:17], v[180:183], v[176:179], v[2:17]
	s_add_u32 m0, vcc_lo, 0x9000
	ds_read_b128 v[74:77], v240 offset:4096
	global_load_lds_dwordx4 v207, s[36:37]
	v_mfma_f32_32x32x16_bf16 v[34:49], v[168:171], v[176:179], v[34:49]
	ds_read_b128 v[78:81], v236 offset:4096
	v_mfma_f32_32x32x16_bf16 v[50:65], v[190:193], v[194:197], v[50:65]
	s_add_u32 m0, vcc_lo, 0xa000
	ds_read_b128 v[82:85], v237
	global_load_lds_dwordx4 v208, s[36:37]
	v_mfma_f32_32x32x16_bf16 v[18:33], v[202:205], v[194:197], v[18:33]
	ds_read_b128 v[86:89], v241
	v_mfma_f32_32x32x16_bf16 v[2:17], v[202:205], v[198:201], v[2:17]
	s_add_u32 m0, vcc_lo, 0xb000
	ds_read_b128 v[90:93], v241 offset:4096
	global_load_lds_dwordx4 v209, s[36:37]
	v_mfma_f32_32x32x16_bf16 v[34:49], v[190:193], v[198:201], v[34:49]
	ds_read_b128 v[94:97], v237 offset:4096
	s_waitcnt lgkmcnt(6)
	v_mfma_f32_32x32x16_bf16 v[50:65], v[66:69], v[70:73], v[50:65]
	s_add_u32 m0, vcc_lo, 0xc000
	ds_read_b128 v[168:171], v238
	global_load_lds_dwordx4 v210, s[38:39]
	s_waitcnt lgkmcnt(5)
	v_mfma_f32_32x32x16_bf16 v[18:33], v[78:81], v[70:73], v[18:33]
	ds_read_b128 v[172:175], v242
	v_mfma_f32_32x32x16_bf16 v[2:17], v[78:81], v[74:77], v[2:17]
	s_add_u32 m0, vcc_lo, 0xd000
	ds_read_b128 v[176:179], v242 offset:4096
	global_load_lds_dwordx4 v211, s[38:39]
	v_mfma_f32_32x32x16_bf16 v[34:49], v[66:69], v[74:77], v[34:49]
	ds_read_b128 v[180:183], v238 offset:4096
	s_waitcnt lgkmcnt(6)
	v_mfma_f32_32x32x16_bf16 v[50:65], v[82:85], v[86:89], v[50:65]
	s_add_u32 m0, vcc_lo, 0xe000
	ds_read_b128 v[190:193], v239
	global_load_lds_dwordx4 v212, s[38:39]
	s_waitcnt lgkmcnt(5)
	v_mfma_f32_32x32x16_bf16 v[18:33], v[94:97], v[86:89], v[18:33]
	ds_read_b128 v[194:197], v243
	v_mfma_f32_32x32x16_bf16 v[2:17], v[94:97], v[90:93], v[2:17]
	s_add_u32 m0, vcc_lo, 0xf000
	ds_read_b128 v[198:201], v243 offset:4096
	global_load_lds_dwordx4 v213, s[38:39]
	v_mfma_f32_32x32x16_bf16 v[34:49], v[82:85], v[90:93], v[34:49]
	ds_read_b128 v[202:205], v239 offset:4096
	s_add_u32 s38, s38, 0x80
	s_addc_u32 s39, s39, 0
	s_waitcnt vmcnt(0) lgkmcnt(0)
	s_barrier
	v_mfma_f32_32x32x16_bf16 v[50:65], v[168:171], v[172:175], v[50:65]
	s_mov_b32 m0, vcc_lo
	ds_read_b128 v[66:69], v236 offset:32768
	global_load_lds_dwordx4 v222, s[40:41]
	s_setprio 3
	v_mfma_f32_32x32x16_bf16 v[18:33], v[180:183], v[172:175], v[18:33]
	ds_read_b128 v[70:73], v240 offset:32768
	v_mfma_f32_32x32x16_bf16 v[2:17], v[180:183], v[176:179], v[2:17]
	s_add_u32 m0, vcc_lo, 0x1000
	ds_read_b128 v[74:77], v240 offset:36864
	global_load_lds_dwordx4 v223, s[40:41]
	v_mfma_f32_32x32x16_bf16 v[34:49], v[168:171], v[176:179], v[34:49]
	ds_read_b128 v[78:81], v236 offset:36864
	v_mfma_f32_32x32x16_bf16 v[50:65], v[190:193], v[194:197], v[50:65]
	s_add_u32 m0, vcc_lo, 0x2000
	ds_read_b128 v[82:85], v237 offset:32768
	global_load_lds_dwordx4 v224, s[40:41]
	v_mfma_f32_32x32x16_bf16 v[18:33], v[202:205], v[194:197], v[18:33]
	ds_read_b128 v[86:89], v241 offset:32768
	v_mfma_f32_32x32x16_bf16 v[2:17], v[202:205], v[198:201], v[2:17]
	s_add_u32 m0, vcc_lo, 0x3000
	ds_read_b128 v[90:93], v241 offset:36864
	global_load_lds_dwordx4 v225, s[40:41]
	v_mfma_f32_32x32x16_bf16 v[34:49], v[190:193], v[198:201], v[34:49]
	ds_read_b128 v[94:97], v237 offset:36864
	s_waitcnt lgkmcnt(6)
	v_mfma_f32_32x32x16_bf16 v[50:65], v[66:69], v[70:73], v[50:65]
	s_add_u32 m0, vcc_lo, 0x4000
	ds_read_b128 v[168:171], v238 offset:32768
	global_load_lds_dwordx4 v222, s[42:43]
	s_waitcnt lgkmcnt(5)
	v_mfma_f32_32x32x16_bf16 v[18:33], v[78:81], v[70:73], v[18:33]
	ds_read_b128 v[172:175], v242 offset:32768
	v_mfma_f32_32x32x16_bf16 v[2:17], v[78:81], v[74:77], v[2:17]
	s_add_u32 m0, vcc_lo, 0x5000
	ds_read_b128 v[176:179], v242 offset:36864
	global_load_lds_dwordx4 v223, s[42:43]
	v_mfma_f32_32x32x16_bf16 v[34:49], v[66:69], v[74:77], v[34:49]
	ds_read_b128 v[180:183], v238 offset:36864
	s_waitcnt lgkmcnt(6)
	v_mfma_f32_32x32x16_bf16 v[50:65], v[82:85], v[86:89], v[50:65]
	s_add_u32 m0, vcc_lo, 0x6000
	ds_read_b128 v[190:193], v239 offset:32768
	global_load_lds_dwordx4 v224, s[42:43]
	s_waitcnt lgkmcnt(5)
	v_mfma_f32_32x32x16_bf16 v[18:33], v[94:97], v[86:89], v[18:33]
	ds_read_b128 v[194:197], v243 offset:32768
	v_mfma_f32_32x32x16_bf16 v[2:17], v[94:97], v[90:93], v[2:17]
	s_add_u32 m0, vcc_lo, 0x7000
	ds_read_b128 v[198:201], v243 offset:36864
	global_load_lds_dwordx4 v225, s[42:43]
	v_mfma_f32_32x32x16_bf16 v[34:49], v[82:85], v[90:93], v[34:49]
	ds_read_b128 v[202:205], v239 offset:36864
	s_add_u32 s40, s40, 0x800
	s_addc_u32 s41, s41, 0
	s_add_u32 s42, s42, 0x800
	s_addc_u32 s43, s43, 0
	s_waitcnt vmcnt(0) lgkmcnt(0)
	s_barrier
	v_mfma_f32_32x32x16_bf16 v[50:65], v[168:171], v[172:175], v[50:65]
	v_mfma_f32_32x32x16_bf16 v[18:33], v[180:183], v[172:175], v[18:33]
	v_mfma_f32_32x32x16_bf16 v[2:17], v[180:183], v[176:179], v[2:17]
	v_mfma_f32_32x32x16_bf16 v[34:49], v[168:171], v[176:179], v[34:49]
	v_mfma_f32_32x32x16_bf16 v[50:65], v[190:193], v[194:197], v[50:65]
	v_mfma_f32_32x32x16_bf16 v[18:33], v[202:205], v[194:197], v[18:33]
	v_mfma_f32_32x32x16_bf16 v[2:17], v[202:205], v[198:201], v[2:17]
	v_mfma_f32_32x32x16_bf16 v[34:49], v[190:193], v[198:201], v[34:49]
	s_setprio 0
	ds_read_u16 v66, v244 offset:0
	ds_read_u16 v67, v244 offset:128
	ds_read_u16 v68, v245 offset:256
	ds_read_u16 v69, v245 offset:384
	ds_read_u16 v70, v244 offset:1088
	ds_read_u16 v71, v244 offset:1216
	ds_read_u16 v72, v245 offset:1344
	ds_read_u16 v73, v245 offset:1472
	s_nop 7
	s_nop 7
	ds_read_u16 v74, v244 offset:2048
	ds_read_u16 v75, v244 offset:2176
	ds_read_u16 v76, v245 offset:2304
	ds_read_u16 v77, v245 offset:2432
	ds_read_u16 v78, v244 offset:3136
	ds_read_u16 v79, v244 offset:3264
	ds_read_u16 v80, v245 offset:3392
	ds_read_u16 v81, v245 offset:3520
	s_waitcnt lgkmcnt(8)
	v_lshlrev_b32_e32 v66, 16, v66
	v_lshlrev_b32_e32 v67, 16, v67
	v_lshlrev_b32_e32 v68, 16, v68
	v_lshlrev_b32_e32 v69, 16, v69
	v_mul_f32_e32 v66, 0xbfb8aa3b, v66
	v_mul_f32_e32 v67, 0xbfb8aa3b, v67
	v_mul_f32_e32 v68, 0xbfb8aa3b, v68
	v_mul_f32_e32 v69, 0xbfb8aa3b, v69
	v_exp_f32_e32 v66, v66
	v_exp_f32_e32 v67, v67
	v_exp_f32_e32 v68, v68
	v_exp_f32_e32 v69, v69
	v_add_f32_e32 v66, 1.0, v66
	v_add_f32_e32 v67, 1.0, v67
	v_add_f32_e32 v68, 1.0, v68
	v_add_f32_e32 v69, 1.0, v69
	v_rcp_f32_e32 v66, v66
	v_rcp_f32_e32 v67, v67
	v_rcp_f32_e32 v68, v68
	v_rcp_f32_e32 v69, v69
	s_nop 0
	v_pk_fma_f32 v[166:167], v[50:51], v[66:67], v[166:167]
	v_pk_fma_f32 v[164:165], v[52:53], v[68:69], v[164:165]
	v_lshlrev_b32_e32 v70, 16, v70
	v_lshlrev_b32_e32 v71, 16, v71
	v_lshlrev_b32_e32 v72, 16, v72
	v_lshlrev_b32_e32 v73, 16, v73
	v_mul_f32_e32 v70, 0xbfb8aa3b, v70
	v_mul_f32_e32 v71, 0xbfb8aa3b, v71
	v_mul_f32_e32 v72, 0xbfb8aa3b, v72
	v_mul_f32_e32 v73, 0xbfb8aa3b, v73
	v_exp_f32_e32 v70, v70
	v_exp_f32_e32 v71, v71
	v_exp_f32_e32 v72, v72
	v_exp_f32_e32 v73, v73
	v_add_f32_e32 v70, 1.0, v70
	v_add_f32_e32 v71, 1.0, v71
	v_add_f32_e32 v72, 1.0, v72
	v_add_f32_e32 v73, 1.0, v73
	v_rcp_f32_e32 v70, v70
	v_rcp_f32_e32 v71, v71
	v_rcp_f32_e32 v72, v72
	v_rcp_f32_e32 v73, v73
	s_nop 0
	v_pk_fma_f32 v[162:163], v[54:55], v[70:71], v[162:163]
	v_pk_fma_f32 v[160:161], v[56:57], v[72:73], v[160:161]
	ds_read_u16 v82, v244 offset:4096
	ds_read_u16 v83, v244 offset:4224
	ds_read_u16 v84, v245 offset:4352
	ds_read_u16 v85, v245 offset:4480
	ds_read_u16 v86, v244 offset:5184
	ds_read_u16 v87, v244 offset:5312
	ds_read_u16 v88, v245 offset:5440
	ds_read_u16 v89, v245 offset:5568
	s_waitcnt lgkmcnt(8)
	v_lshlrev_b32_e32 v74, 16, v74
	v_lshlrev_b32_e32 v75, 16, v75
	v_lshlrev_b32_e32 v76, 16, v76
	v_lshlrev_b32_e32 v77, 16, v77
	v_mul_f32_e32 v74, 0xbfb8aa3b, v74
	v_mul_f32_e32 v75, 0xbfb8aa3b, v75
	v_mul_f32_e32 v76, 0xbfb8aa3b, v76
	v_mul_f32_e32 v77, 0xbfb8aa3b, v77
	v_exp_f32_e32 v74, v74
	v_exp_f32_e32 v75, v75
	v_exp_f32_e32 v76, v76
	v_exp_f32_e32 v77, v77
	v_add_f32_e32 v74, 1.0, v74
	v_add_f32_e32 v75, 1.0, v75
	v_add_f32_e32 v76, 1.0, v76
	v_add_f32_e32 v77, 1.0, v77
	v_rcp_f32_e32 v74, v74
	v_rcp_f32_e32 v75, v75
	v_rcp_f32_e32 v76, v76
	v_rcp_f32_e32 v77, v77
	s_nop 0
	v_pk_fma_f32 v[158:159], v[58:59], v[74:75], v[158:159]
	v_pk_fma_f32 v[156:157], v[60:61], v[76:77], v[156:157]
	v_lshlrev_b32_e32 v78, 16, v78
	v_lshlrev_b32_e32 v79, 16, v79
	v_lshlrev_b32_e32 v80, 16, v80
	v_lshlrev_b32_e32 v81, 16, v81
	v_mul_f32_e32 v78, 0xbfb8aa3b, v78
	v_mul_f32_e32 v79, 0xbfb8aa3b, v79
	v_mul_f32_e32 v80, 0xbfb8aa3b, v80
	v_mul_f32_e32 v81, 0xbfb8aa3b, v81
	v_exp_f32_e32 v78, v78
	v_exp_f32_e32 v79, v79
	v_exp_f32_e32 v80, v80
	v_exp_f32_e32 v81, v81
	v_add_f32_e32 v78, 1.0, v78
	v_add_f32_e32 v79, 1.0, v79
	v_add_f32_e32 v80, 1.0, v80
	v_add_f32_e32 v81, 1.0, v81
	v_rcp_f32_e32 v78, v78
	v_rcp_f32_e32 v79, v79
	v_rcp_f32_e32 v80, v80
	v_rcp_f32_e32 v81, v81
	s_nop 0
	v_pk_fma_f32 v[154:155], v[62:63], v[78:79], v[154:155]
	v_pk_fma_f32 v[152:153], v[64:65], v[80:81], v[152:153]
	ds_read_u16 v90, v244 offset:6144
	ds_read_u16 v91, v244 offset:6272
	ds_read_u16 v92, v245 offset:6400
	ds_read_u16 v93, v245 offset:6528
	ds_read_u16 v94, v244 offset:7232
	ds_read_u16 v95, v244 offset:7360
	ds_read_u16 v96, v245 offset:7488
	ds_read_u16 v97, v245 offset:7616
	s_waitcnt lgkmcnt(8)
	v_lshlrev_b32_e32 v82, 16, v82
	v_lshlrev_b32_e32 v83, 16, v83
	v_lshlrev_b32_e32 v84, 16, v84
	v_lshlrev_b32_e32 v85, 16, v85
	v_mul_f32_e32 v82, 0xbfb8aa3b, v82
	v_mul_f32_e32 v83, 0xbfb8aa3b, v83
	v_mul_f32_e32 v84, 0xbfb8aa3b, v84
	v_mul_f32_e32 v85, 0xbfb8aa3b, v85
	v_exp_f32_e32 v82, v82
	v_exp_f32_e32 v83, v83
	v_exp_f32_e32 v84, v84
	v_exp_f32_e32 v85, v85
	v_add_f32_e32 v82, 1.0, v82
	v_add_f32_e32 v83, 1.0, v83
	v_add_f32_e32 v84, 1.0, v84
	v_add_f32_e32 v85, 1.0, v85
	v_rcp_f32_e32 v82, v82
	v_rcp_f32_e32 v83, v83
	v_rcp_f32_e32 v84, v84
	v_rcp_f32_e32 v85, v85
	s_nop 0
	v_pk_fma_f32 v[130:131], v[18:19], v[82:83], v[130:131]
	v_pk_fma_f32 v[128:129], v[20:21], v[84:85], v[128:129]
	v_lshlrev_b32_e32 v86, 16, v86
	v_lshlrev_b32_e32 v87, 16, v87
	v_lshlrev_b32_e32 v88, 16, v88
	v_lshlrev_b32_e32 v89, 16, v89
	v_mul_f32_e32 v86, 0xbfb8aa3b, v86
	v_mul_f32_e32 v87, 0xbfb8aa3b, v87
	v_mul_f32_e32 v88, 0xbfb8aa3b, v88
	v_mul_f32_e32 v89, 0xbfb8aa3b, v89
	v_exp_f32_e32 v86, v86
	v_exp_f32_e32 v87, v87
	v_exp_f32_e32 v88, v88
	v_exp_f32_e32 v89, v89
	v_add_f32_e32 v86, 1.0, v86
	v_add_f32_e32 v87, 1.0, v87
	v_add_f32_e32 v88, 1.0, v88
	v_add_f32_e32 v89, 1.0, v89
	v_rcp_f32_e32 v86, v86
	v_rcp_f32_e32 v87, v87
	v_rcp_f32_e32 v88, v88
	v_rcp_f32_e32 v89, v89
	s_nop 0
	v_pk_fma_f32 v[126:127], v[22:23], v[86:87], v[126:127]
	v_pk_fma_f32 v[124:125], v[24:25], v[88:89], v[124:125]
	ds_read_u16 v168, v244 offset:4160
	ds_read_u16 v169, v244 offset:4288
	ds_read_u16 v170, v245 offset:4416
	ds_read_u16 v171, v245 offset:4544
	ds_read_u16 v172, v244 offset:5120
	ds_read_u16 v173, v244 offset:5248
	ds_read_u16 v174, v245 offset:5376
	ds_read_u16 v175, v245 offset:5504
	s_waitcnt lgkmcnt(8)
	v_lshlrev_b32_e32 v90, 16, v90
	v_lshlrev_b32_e32 v91, 16, v91
	v_lshlrev_b32_e32 v92, 16, v92
	v_lshlrev_b32_e32 v93, 16, v93
	v_mul_f32_e32 v90, 0xbfb8aa3b, v90
	v_mul_f32_e32 v91, 0xbfb8aa3b, v91
	v_mul_f32_e32 v92, 0xbfb8aa3b, v92
	v_mul_f32_e32 v93, 0xbfb8aa3b, v93
	v_exp_f32_e32 v90, v90
	v_exp_f32_e32 v91, v91
	v_exp_f32_e32 v92, v92
	v_exp_f32_e32 v93, v93
	v_add_f32_e32 v90, 1.0, v90
	v_add_f32_e32 v91, 1.0, v91
	v_add_f32_e32 v92, 1.0, v92
	v_add_f32_e32 v93, 1.0, v93
	v_rcp_f32_e32 v90, v90
	v_rcp_f32_e32 v91, v91
	v_rcp_f32_e32 v92, v92
	v_rcp_f32_e32 v93, v93
	s_nop 0
	v_pk_fma_f32 v[122:123], v[26:27], v[90:91], v[122:123]
	v_pk_fma_f32 v[120:121], v[28:29], v[92:93], v[120:121]
	v_lshlrev_b32_e32 v94, 16, v94
	v_lshlrev_b32_e32 v95, 16, v95
	v_lshlrev_b32_e32 v96, 16, v96
	v_lshlrev_b32_e32 v97, 16, v97
	v_mul_f32_e32 v94, 0xbfb8aa3b, v94
	v_mul_f32_e32 v95, 0xbfb8aa3b, v95
	v_mul_f32_e32 v96, 0xbfb8aa3b, v96
	v_mul_f32_e32 v97, 0xbfb8aa3b, v97
	v_exp_f32_e32 v94, v94
	v_exp_f32_e32 v95, v95
	v_exp_f32_e32 v96, v96
	v_exp_f32_e32 v97, v97
	v_add_f32_e32 v94, 1.0, v94
	v_add_f32_e32 v95, 1.0, v95
	v_add_f32_e32 v96, 1.0, v96
	v_add_f32_e32 v97, 1.0, v97
	v_rcp_f32_e32 v94, v94
	v_rcp_f32_e32 v95, v95
	v_rcp_f32_e32 v96, v96
	v_rcp_f32_e32 v97, v97
	s_nop 0
	v_pk_fma_f32 v[118:119], v[30:31], v[94:95], v[118:119]
	v_pk_fma_f32 v[116:117], v[32:33], v[96:97], v[116:117]
	ds_read_u16 v176, v244 offset:6208
	ds_read_u16 v177, v244 offset:6336
	ds_read_u16 v178, v245 offset:6464
	ds_read_u16 v179, v245 offset:6592
	ds_read_u16 v180, v244 offset:7168
	ds_read_u16 v181, v244 offset:7296
	ds_read_u16 v182, v245 offset:7424
	ds_read_u16 v183, v245 offset:7552
	s_waitcnt lgkmcnt(8)
	v_lshlrev_b32_e32 v168, 16, v168
	v_lshlrev_b32_e32 v169, 16, v169
	v_lshlrev_b32_e32 v170, 16, v170
	v_lshlrev_b32_e32 v171, 16, v171
	v_mul_f32_e32 v168, 0xbfb8aa3b, v168
	v_mul_f32_e32 v169, 0xbfb8aa3b, v169
	v_mul_f32_e32 v170, 0xbfb8aa3b, v170
	v_mul_f32_e32 v171, 0xbfb8aa3b, v171
	v_exp_f32_e32 v168, v168
	v_exp_f32_e32 v169, v169
	v_exp_f32_e32 v170, v170
	v_exp_f32_e32 v171, v171
	v_add_f32_e32 v168, 1.0, v168
	v_add_f32_e32 v169, 1.0, v169
	v_add_f32_e32 v170, 1.0, v170
	v_add_f32_e32 v171, 1.0, v171
	v_rcp_f32_e32 v168, v168
	v_rcp_f32_e32 v169, v169
	v_rcp_f32_e32 v170, v170
	v_rcp_f32_e32 v171, v171
	s_nop 0
	v_pk_fma_f32 v[114:115], v[2:3], v[168:169], v[114:115]
	v_pk_fma_f32 v[112:113], v[4:5], v[170:171], v[112:113]
	v_lshlrev_b32_e32 v172, 16, v172
	v_lshlrev_b32_e32 v173, 16, v173
	v_lshlrev_b32_e32 v174, 16, v174
	v_lshlrev_b32_e32 v175, 16, v175
	v_mul_f32_e32 v172, 0xbfb8aa3b, v172
	v_mul_f32_e32 v173, 0xbfb8aa3b, v173
	v_mul_f32_e32 v174, 0xbfb8aa3b, v174
	v_mul_f32_e32 v175, 0xbfb8aa3b, v175
	v_exp_f32_e32 v172, v172
	v_exp_f32_e32 v173, v173
	v_exp_f32_e32 v174, v174
	v_exp_f32_e32 v175, v175
	v_add_f32_e32 v172, 1.0, v172
	v_add_f32_e32 v173, 1.0, v173
	v_add_f32_e32 v174, 1.0, v174
	v_add_f32_e32 v175, 1.0, v175
	v_rcp_f32_e32 v172, v172
	v_rcp_f32_e32 v173, v173
	v_rcp_f32_e32 v174, v174
	v_rcp_f32_e32 v175, v175
	s_nop 0
	v_pk_fma_f32 v[110:111], v[6:7], v[172:173], v[110:111]
	v_pk_fma_f32 v[108:109], v[8:9], v[174:175], v[108:109]
	ds_read_u16 v190, v244 offset:64
	ds_read_u16 v191, v244 offset:192
	ds_read_u16 v192, v245 offset:320
	ds_read_u16 v193, v245 offset:448
	ds_read_u16 v194, v244 offset:1024
	ds_read_u16 v195, v244 offset:1152
	ds_read_u16 v196, v245 offset:1280
	ds_read_u16 v197, v245 offset:1408
	s_waitcnt lgkmcnt(8)
	v_lshlrev_b32_e32 v176, 16, v176
	v_lshlrev_b32_e32 v177, 16, v177
	v_lshlrev_b32_e32 v178, 16, v178
	v_lshlrev_b32_e32 v179, 16, v179
	v_mul_f32_e32 v176, 0xbfb8aa3b, v176
	v_mul_f32_e32 v177, 0xbfb8aa3b, v177
	v_mul_f32_e32 v178, 0xbfb8aa3b, v178
	v_mul_f32_e32 v179, 0xbfb8aa3b, v179
	v_exp_f32_e32 v176, v176
	v_exp_f32_e32 v177, v177
	v_exp_f32_e32 v178, v178
	v_exp_f32_e32 v179, v179
	v_add_f32_e32 v176, 1.0, v176
	v_add_f32_e32 v177, 1.0, v177
	v_add_f32_e32 v178, 1.0, v178
	v_add_f32_e32 v179, 1.0, v179
	v_rcp_f32_e32 v176, v176
	v_rcp_f32_e32 v177, v177
	v_rcp_f32_e32 v178, v178
	v_rcp_f32_e32 v179, v179
	s_nop 0
	v_pk_fma_f32 v[106:107], v[10:11], v[176:177], v[106:107]
	v_pk_fma_f32 v[104:105], v[12:13], v[178:179], v[104:105]
	v_lshlrev_b32_e32 v180, 16, v180
	v_lshlrev_b32_e32 v181, 16, v181
	v_lshlrev_b32_e32 v182, 16, v182
	v_lshlrev_b32_e32 v183, 16, v183
	v_mul_f32_e32 v180, 0xbfb8aa3b, v180
	v_mul_f32_e32 v181, 0xbfb8aa3b, v181
	v_mul_f32_e32 v182, 0xbfb8aa3b, v182
	v_mul_f32_e32 v183, 0xbfb8aa3b, v183
	v_exp_f32_e32 v180, v180
	v_exp_f32_e32 v181, v181
	v_exp_f32_e32 v182, v182
	v_exp_f32_e32 v183, v183
	v_add_f32_e32 v180, 1.0, v180
	v_add_f32_e32 v181, 1.0, v181
	v_add_f32_e32 v182, 1.0, v182
	v_add_f32_e32 v183, 1.0, v183
	v_rcp_f32_e32 v180, v180
	v_rcp_f32_e32 v181, v181
	v_rcp_f32_e32 v182, v182
	v_rcp_f32_e32 v183, v183
	s_nop 0
	v_pk_fma_f32 v[102:103], v[14:15], v[180:181], v[102:103]
	v_pk_fma_f32 v[100:101], v[16:17], v[182:183], v[100:101]
	ds_read_u16 v198, v244 offset:2112
	ds_read_u16 v199, v244 offset:2240
	ds_read_u16 v200, v245 offset:2368
	ds_read_u16 v201, v245 offset:2496
	ds_read_u16 v202, v244 offset:3072
	ds_read_u16 v203, v244 offset:3200
	ds_read_u16 v204, v245 offset:3328
	ds_read_u16 v205, v245 offset:3456
	s_waitcnt lgkmcnt(8)
	v_lshlrev_b32_e32 v190, 16, v190
	v_lshlrev_b32_e32 v191, 16, v191
	v_lshlrev_b32_e32 v192, 16, v192
	v_lshlrev_b32_e32 v193, 16, v193
	v_mul_f32_e32 v190, 0xbfb8aa3b, v190
	v_mul_f32_e32 v191, 0xbfb8aa3b, v191
	v_mul_f32_e32 v192, 0xbfb8aa3b, v192
	v_mul_f32_e32 v193, 0xbfb8aa3b, v193
	v_exp_f32_e32 v190, v190
	v_exp_f32_e32 v191, v191
	v_exp_f32_e32 v192, v192
	v_exp_f32_e32 v193, v193
	v_add_f32_e32 v190, 1.0, v190
	v_add_f32_e32 v191, 1.0, v191
	v_add_f32_e32 v192, 1.0, v192
	v_add_f32_e32 v193, 1.0, v193
	v_rcp_f32_e32 v190, v190
	v_rcp_f32_e32 v191, v191
	v_rcp_f32_e32 v192, v192
	v_rcp_f32_e32 v193, v193
	s_nop 0
	v_pk_fma_f32 v[150:151], v[34:35], v[190:191], v[150:151]
	v_pk_fma_f32 v[148:149], v[36:37], v[192:193], v[148:149]
	v_lshlrev_b32_e32 v194, 16, v194
	v_lshlrev_b32_e32 v195, 16, v195
	v_lshlrev_b32_e32 v196, 16, v196
	v_lshlrev_b32_e32 v197, 16, v197
	v_mul_f32_e32 v194, 0xbfb8aa3b, v194
	v_mul_f32_e32 v195, 0xbfb8aa3b, v195
	v_mul_f32_e32 v196, 0xbfb8aa3b, v196
	v_mul_f32_e32 v197, 0xbfb8aa3b, v197
	v_exp_f32_e32 v194, v194
	v_exp_f32_e32 v195, v195
	v_exp_f32_e32 v196, v196
	v_exp_f32_e32 v197, v197
	v_add_f32_e32 v194, 1.0, v194
	v_add_f32_e32 v195, 1.0, v195
	v_add_f32_e32 v196, 1.0, v196
	v_add_f32_e32 v197, 1.0, v197
	v_rcp_f32_e32 v194, v194
	v_rcp_f32_e32 v195, v195
	v_rcp_f32_e32 v196, v196
	v_rcp_f32_e32 v197, v197
	s_nop 0
	v_pk_fma_f32 v[146:147], v[38:39], v[194:195], v[146:147]
	v_pk_fma_f32 v[142:143], v[40:41], v[196:197], v[142:143]
	s_waitcnt lgkmcnt(0)
	v_lshlrev_b32_e32 v198, 16, v198
	v_lshlrev_b32_e32 v199, 16, v199
	v_lshlrev_b32_e32 v200, 16, v200
	v_lshlrev_b32_e32 v201, 16, v201
	v_mul_f32_e32 v198, 0xbfb8aa3b, v198
	v_mul_f32_e32 v199, 0xbfb8aa3b, v199
	v_mul_f32_e32 v200, 0xbfb8aa3b, v200
	v_mul_f32_e32 v201, 0xbfb8aa3b, v201
	v_exp_f32_e32 v198, v198
	v_exp_f32_e32 v199, v199
	v_exp_f32_e32 v200, v200
	v_exp_f32_e32 v201, v201
	v_add_f32_e32 v198, 1.0, v198
	v_add_f32_e32 v199, 1.0, v199
	v_add_f32_e32 v200, 1.0, v200
	v_add_f32_e32 v201, 1.0, v201
	v_rcp_f32_e32 v198, v198
	v_rcp_f32_e32 v199, v199
	v_rcp_f32_e32 v200, v200
	v_rcp_f32_e32 v201, v201
	s_nop 0
	v_pk_fma_f32 v[140:141], v[42:43], v[198:199], v[140:141]
	v_pk_fma_f32 v[138:139], v[44:45], v[200:201], v[138:139]
	v_lshlrev_b32_e32 v202, 16, v202
	v_lshlrev_b32_e32 v203, 16, v203
	v_lshlrev_b32_e32 v204, 16, v204
	v_lshlrev_b32_e32 v205, 16, v205
	v_mul_f32_e32 v202, 0xbfb8aa3b, v202
	v_mul_f32_e32 v203, 0xbfb8aa3b, v203
	v_mul_f32_e32 v204, 0xbfb8aa3b, v204
	v_mul_f32_e32 v205, 0xbfb8aa3b, v205
	v_exp_f32_e32 v202, v202
	v_exp_f32_e32 v203, v203
	v_exp_f32_e32 v204, v204
	v_exp_f32_e32 v205, v205
	v_add_f32_e32 v202, 1.0, v202
	v_add_f32_e32 v203, 1.0, v203
	v_add_f32_e32 v204, 1.0, v204
	v_add_f32_e32 v205, 1.0, v205
	v_rcp_f32_e32 v202, v202
	v_rcp_f32_e32 v203, v203
	v_rcp_f32_e32 v204, v204
	v_rcp_f32_e32 v205, v205
	s_nop 0
	v_pk_fma_f32 v[136:137], v[46:47], v[202:203], v[136:137]
	v_pk_fma_f32 v[134:135], v[48:49], v[204:205], v[134:135]
	v_readlane_b32 s36, v252, 4
	v_readlane_b32 s37, v252, 5
	v_readlane_b32 s38, v252, 6
	v_readlane_b32 s39, v252, 7
	v_readlane_b32 s40, v252, 8
	v_readlane_b32 s41, v252, 9
	v_readlane_b32 s42, v252, 10
	v_readlane_b32 s43, v252, 11
	v_readlane_b32 s44, v252, 12
	v_readlane_b32 s45, v252, 13
	v_readlane_b32 s46, v252, 14
	v_readlane_b32 s47, v252, 15
	v_readlane_b32 s48, v252, 16
	v_readlane_b32 s49, v252, 17
	s_mov_b32 s94, 0x9425000
	s_mov_b32 s25, 0xa8000
	s_movk_i32 s26, 0x600
	s_movk_i32 s27, 0x80
	v_cvt_pk_bf16_f32 v0, v166, s0
	s_barrier
	ds_write_b16 v98, v0
	v_cvt_pk_bf16_f32 v0, v167, s0
	ds_write_b16 v98, v0 offset:272
	v_cvt_pk_bf16_f32 v0, v164, s0
	ds_write_b16 v98, v0 offset:544
	v_cvt_pk_bf16_f32 v0, v165, s0
	ds_write_b16 v98, v0 offset:816
	v_cvt_pk_bf16_f32 v0, v162, s0
	ds_write_b16 v98, v0 offset:2176
	v_cvt_pk_bf16_f32 v0, v163, s0
	ds_write_b16 v98, v0 offset:2448
	v_cvt_pk_bf16_f32 v0, v160, s0
	ds_write_b16 v98, v0 offset:2720
	v_cvt_pk_bf16_f32 v0, v161, s0
	ds_write_b16 v98, v0 offset:2992
	v_cvt_pk_bf16_f32 v0, v158, s0
	ds_write_b16 v98, v0 offset:4352
	v_cvt_pk_bf16_f32 v0, v159, s0
	ds_write_b16 v98, v0 offset:4624
	v_cvt_pk_bf16_f32 v0, v156, s0
	ds_write_b16 v98, v0 offset:4896
	v_cvt_pk_bf16_f32 v0, v157, s0
	ds_write_b16 v98, v0 offset:5168
	v_cvt_pk_bf16_f32 v0, v154, s0
	ds_write_b16 v98, v0 offset:6528
	v_cvt_pk_bf16_f32 v0, v155, s0
	ds_write_b16 v98, v0 offset:6800
	v_cvt_pk_bf16_f32 v0, v152, s0
	ds_write_b16 v98, v0 offset:7072
	v_cvt_pk_bf16_f32 v0, v153, s0
	ds_write_b16 v98, v0 offset:7344
	v_cvt_pk_bf16_f32 v0, v150, s0
	ds_write_b16 v98, v0 offset:64
	v_cvt_pk_bf16_f32 v0, v151, s0
	ds_write_b16 v98, v0 offset:336
	v_cvt_pk_bf16_f32 v0, v148, s0
	ds_write_b16 v98, v0 offset:608
	v_cvt_pk_bf16_f32 v0, v149, s0
	ds_write_b16 v98, v0 offset:880
	v_cvt_pk_bf16_f32 v0, v146, s0
	ds_write_b16 v98, v0 offset:2240
	v_cvt_pk_bf16_f32 v0, v147, s0
	ds_write_b16 v98, v0 offset:2512
	v_cvt_pk_bf16_f32 v0, v142, s0
	ds_write_b16 v98, v0 offset:2784
	v_cvt_pk_bf16_f32 v0, v143, s0
	ds_write_b16 v98, v0 offset:3056
	v_cvt_pk_bf16_f32 v0, v140, s0
	ds_write_b16 v98, v0 offset:4416
	v_cvt_pk_bf16_f32 v0, v141, s0
	ds_write_b16 v98, v0 offset:4688
	v_cvt_pk_bf16_f32 v0, v138, s0
	ds_write_b16 v98, v0 offset:4960
	v_cvt_pk_bf16_f32 v0, v139, s0
	ds_write_b16 v98, v0 offset:5232
	v_cvt_pk_bf16_f32 v0, v136, s0
	ds_write_b16 v98, v0 offset:6592
	v_cvt_pk_bf16_f32 v0, v137, s0
	ds_write_b16 v98, v0 offset:6864
	v_cvt_pk_bf16_f32 v0, v134, s0
	ds_write_b16 v98, v0 offset:7136
	v_cvt_pk_bf16_f32 v0, v135, s0
	ds_write_b16 v98, v0 offset:7408
	v_cvt_pk_bf16_f32 v0, v130, s0
	ds_write_b16 v98, v0 offset:8704
	v_cvt_pk_bf16_f32 v0, v131, s0
	ds_write_b16 v98, v0 offset:8976
	v_cvt_pk_bf16_f32 v0, v128, s0
	ds_write_b16 v98, v0 offset:9248
	v_cvt_pk_bf16_f32 v0, v129, s0
	ds_write_b16 v98, v0 offset:9520
	v_cvt_pk_bf16_f32 v0, v126, s0
	ds_write_b16 v98, v0 offset:10880
	v_cvt_pk_bf16_f32 v0, v127, s0
	ds_write_b16 v98, v0 offset:11152
	v_cvt_pk_bf16_f32 v0, v124, s0
	ds_write_b16 v98, v0 offset:11424
	v_cvt_pk_bf16_f32 v0, v125, s0
	ds_write_b16 v98, v0 offset:11696
	v_cvt_pk_bf16_f32 v0, v122, s0
	ds_write_b16 v98, v0 offset:13056
	v_cvt_pk_bf16_f32 v0, v123, s0
	ds_write_b16 v98, v0 offset:13328
	v_cvt_pk_bf16_f32 v0, v120, s0
	ds_write_b16 v98, v0 offset:13600
	v_cvt_pk_bf16_f32 v0, v121, s0
	ds_write_b16 v98, v0 offset:13872
	v_cvt_pk_bf16_f32 v0, v118, s0
	ds_write_b16 v98, v0 offset:15232
	v_cvt_pk_bf16_f32 v0, v119, s0
	ds_write_b16 v98, v0 offset:15504
	v_cvt_pk_bf16_f32 v0, v116, s0
	ds_write_b16 v98, v0 offset:15776
	v_cvt_pk_bf16_f32 v0, v117, s0
	ds_write_b16 v98, v0 offset:16048
	v_cvt_pk_bf16_f32 v0, v114, s0
	ds_write_b16 v98, v0 offset:8768
	v_cvt_pk_bf16_f32 v0, v115, s0
	ds_write_b16 v98, v0 offset:9040
	v_cvt_pk_bf16_f32 v0, v112, s0
	ds_write_b16 v98, v0 offset:9312
	v_cvt_pk_bf16_f32 v0, v113, s0
	ds_write_b16 v98, v0 offset:9584
	v_cvt_pk_bf16_f32 v0, v110, s0
	ds_write_b16 v98, v0 offset:10944
	v_cvt_pk_bf16_f32 v0, v111, s0
	ds_write_b16 v98, v0 offset:11216
	v_cvt_pk_bf16_f32 v0, v108, s0
	ds_write_b16 v98, v0 offset:11488
	v_cvt_pk_bf16_f32 v0, v109, s0
	ds_write_b16 v98, v0 offset:11760
	v_cvt_pk_bf16_f32 v0, v106, s0
	ds_write_b16 v98, v0 offset:13120
	v_cvt_pk_bf16_f32 v0, v107, s0
	ds_write_b16 v98, v0 offset:13392
	v_cvt_pk_bf16_f32 v0, v104, s0
	ds_write_b16 v98, v0 offset:13664
	v_cvt_pk_bf16_f32 v0, v105, s0
	ds_write_b16 v98, v0 offset:13936
	v_cvt_pk_bf16_f32 v0, v102, s0
	ds_write_b16 v98, v0 offset:15296
	v_cvt_pk_bf16_f32 v0, v103, s0
	ds_write_b16 v98, v0 offset:15568
	v_cvt_pk_bf16_f32 v0, v100, s0
	ds_write_b16 v98, v0 offset:15840
	v_cvt_pk_bf16_f32 v0, v101, s0
	ds_write_b16 v98, v0 offset:16112
	s_waitcnt lgkmcnt(0)
	s_barrier
	ds_read_b128 v[2:5], v133
	ds_read_b128 v[6:9], v133 offset:4352
	s_lshl_b32 s24, s22, 7
	s_and_b32 s24, s24, 0x380
	v_add_lshl_u32 v0, v184, s23, 10
	v_or3_b32 v0, v185, s24, v0
	v_lshl_add_u64 v[10:11], v[0:1], 1, s[72:73]
	s_waitcnt lgkmcnt(1)
	global_store_dwordx4 v[10:11], v[2:5], off
	v_readlane_b32 s23, v254, 37
	s_add_i32 s20, s20, s23
	v_add_u32_e32 v2, 0x4000, v0
	v_mov_b32_e32 v3, v1
	v_lshl_add_u64 v[2:3], v[2:3], 1, s[72:73]
	s_waitcnt lgkmcnt(0)
	global_store_dwordx4 v[2:3], v[6:9], off
	ds_read_b128 v[2:5], v133 offset:8704
	v_readlane_b32 s23, v254, 36
	v_add_u32_e32 v6, 0x8000, v0
	v_mov_b32_e32 v7, v1
	v_lshl_add_u64 v[10:11], v[6:7], 1, s[72:73]
	ds_read_b128 v[6:9], v133 offset:13056
	s_waitcnt lgkmcnt(1)
	global_store_dwordx4 v[10:11], v[2:5], off
	s_add_i32 s22, s22, s81
	s_add_i32 s21, s21, s23
	v_add_u32_e32 v2, 0xc000, v0
	v_mov_b32_e32 v3, v1
	v_lshl_add_u64 v[2:3], v[2:3], 1, s[72:73]
	s_waitcnt lgkmcnt(0)
	global_store_dwordx4 v[2:3], v[6:9], off
	ds_read_b128 v[2:5], v133 offset:17408
	s_cmpk_gt_i32 s22, 0x1ff
	v_add_u32_e32 v6, 0x10000, v0
	v_mov_b32_e32 v7, v1
	v_lshl_add_u64 v[10:11], v[6:7], 1, s[72:73]
	ds_read_b128 v[6:9], v133 offset:21760
	s_waitcnt lgkmcnt(1)
	global_store_dwordx4 v[10:11], v[2:5], off
	s_nop 1
	v_add_u32_e32 v2, 0x14000, v0
	v_mov_b32_e32 v3, v1
	v_lshl_add_u64 v[2:3], v[2:3], 1, s[72:73]
	s_waitcnt lgkmcnt(0)
	global_store_dwordx4 v[2:3], v[6:9], off
	ds_read_b128 v[2:5], v133 offset:26112
	s_nop 0
	v_add_u32_e32 v6, 0x18000, v0
	v_mov_b32_e32 v7, v1
	v_lshl_add_u64 v[10:11], v[6:7], 1, s[72:73]
	ds_read_b128 v[6:9], v133 offset:30464
	v_add_u32_e32 v0, 0x1c000, v0
	s_waitcnt lgkmcnt(1)
	global_store_dwordx4 v[10:11], v[2:5], off
	s_nop 1
	v_lshl_add_u64 v[2:3], v[0:1], 1, s[72:73]
	s_waitcnt lgkmcnt(0)
	global_store_dwordx4 v[2:3], v[6:9], off
	s_cbranch_scc0 .LBB0_212
	s_mov_b32 s19, 0x80000
	s_mov_b32 s14, 0xdb629599
	s_mov_b32 s15, 0xf534ddc0
	s_mov_b32 s16, 0xfc2757d1
	s_mov_b64 s[12:13], s[30:31]
	v_readlane_b32 s22, v255, 2
	v_mov_b32_e32 v187, 0x358637bd
	v_mov_b32_e32 v196, v189
	v_mov_b32_e32 v197, v214
	v_mov_b32_e32 v198, v215
	v_mov_b32_e32 v199, v218
	v_xor_b32_e32 v200, 16, v220
	v_xor_b32_e32 v201, 8, v220
	v_mov_b32_e32 v202, v219
	v_mov_b32_e32 v203, v229
	v_mov_b32_e32 v204, v230
	v_readlane_b32 s23, v255, 3
